# adjacent s_setprio 0/s_setprio 1 pairs between the two MMA halves of each GEMM phase removed
# baseline (speedup 1.0000x reference)
.LBB0_245:
	s_add_u32 s18, s16, 0x100
	s_addc_u32 s19, s17, 0
	s_add_i32 s53, 0, 0x10000
	v_add_u32_e32 v94, s53, v80
	ds_read_b128 v[82:85], v94
	ds_read_b128 v[86:89], v94 offset:1024
	ds_read_b128 v[90:93], v94 offset:2048
	ds_read_b128 v[94:97], v94 offset:3072
	s_cmp_eq_u32 s52, 4
	s_cselect_b32 s23, s9, s19
	s_cselect_b32 s22, s8, s18
	s_cselect_b32 s21, s15, s47
	s_cselect_b32 s20, s45, s46
	v_lshl_add_u64 v[130:131], s[16:17], 0, v[76:77]
	s_add_i32 m0, s29, 0xc000
	ds_read_b128 v[98:101], v81
	ds_read_b128 v[102:105], v81 offset:1024
	ds_read_b128 v[106:109], v81 offset:2048
	ds_read_b128 v[110:113], v81 offset:3072
	ds_read_b128 v[114:117], v81 offset:4096
	ds_read_b128 v[118:121], v81 offset:5120
	ds_read_b128 v[122:125], v81 offset:6144
	ds_read_b128 v[126:129], v81 offset:7168
	global_load_lds_dwordx4 v[130:131], off
	v_lshl_add_u64 v[130:131], s[16:17], 0, v[78:79]
	s_add_i32 m0, s29, 0xe000
	s_nop 0
	global_load_lds_dwordx4 v[130:131], off
	s_waitcnt vmcnt(8)
	s_waitcnt lgkmcnt(0)
	s_barrier
	s_setprio 1
	v_mfma_f32_16x16x32_bf16 v[62:65], v[82:85], v[98:101], v[62:65]
	v_mfma_f32_16x16x32_bf16 v[58:61], v[90:93], v[98:101], v[58:61]
	v_mfma_f32_16x16x32_bf16 v[54:57], v[82:85], v[106:109], v[54:57]
	v_mfma_f32_16x16x32_bf16 v[50:53], v[90:93], v[106:109], v[50:53]
	v_mfma_f32_16x16x32_bf16 v[46:49], v[82:85], v[114:117], v[46:49]
	v_mfma_f32_16x16x32_bf16 v[42:45], v[90:93], v[114:117], v[42:45]
	v_mfma_f32_16x16x32_bf16 v[38:41], v[82:85], v[122:125], v[38:41]
	v_mfma_f32_16x16x32_bf16 v[34:37], v[90:93], v[122:125], v[34:37]
	v_mfma_f32_16x16x32_bf16 v[62:65], v[86:89], v[102:105], v[62:65]
	v_mfma_f32_16x16x32_bf16 v[58:61], v[94:97], v[102:105], v[58:61]
	v_mfma_f32_16x16x32_bf16 v[54:57], v[86:89], v[110:113], v[54:57]
	v_mfma_f32_16x16x32_bf16 v[50:53], v[94:97], v[110:113], v[50:53]
	v_mfma_f32_16x16x32_bf16 v[46:49], v[86:89], v[118:121], v[46:49]
	v_mfma_f32_16x16x32_bf16 v[42:45], v[94:97], v[118:121], v[42:45]
	v_mfma_f32_16x16x32_bf16 v[38:41], v[86:89], v[126:129], v[38:41]
	v_mfma_f32_16x16x32_bf16 v[34:37], v[94:97], v[126:129], v[34:37]
	s_setprio 0
	s_barrier
	s_add_i32 s16, s53, s28
	v_lshl_add_u64 v[130:131], s[20:21], 0, v[70:71]
	s_mov_b32 m0, s16
	ds_read_b128 v[98:101], v81 offset:16384
	ds_read_b128 v[102:105], v81 offset:17408
	ds_read_b128 v[106:109], v81 offset:18432
	ds_read_b128 v[110:113], v81 offset:19456
	ds_read_b128 v[114:117], v81 offset:20480
	ds_read_b128 v[118:121], v81 offset:21504
	ds_read_b128 v[122:125], v81 offset:22528
	ds_read_b128 v[126:129], v81 offset:23552
	global_load_lds_dwordx4 v[130:131], off
	s_add_i32 m0, s16, 0x2000
	s_add_u32 s16, s20, 0x20000
	v_lshl_add_u64 v[132:133], s[20:21], 0, v[66:67]
	s_addc_u32 s17, s21, 0
	global_load_lds_dwordx4 v[132:133], off
	v_lshl_add_u64 v[134:135], s[16:17], 0, v[70:71]
	s_mov_b32 m0, s30
	v_lshl_add_u64 v[136:137], s[22:23], 0, v[68:69]
	global_load_lds_dwordx4 v[134:135], off
	v_lshl_add_u64 v[134:135], s[16:17], 0, v[66:67]
	s_mov_b32 m0, s31
	s_nop 0
	global_load_lds_dwordx4 v[134:135], off
	v_lshl_add_u64 v[134:135], s[22:23], 0, v[72:73]
	s_mov_b32 m0, s29
	s_nop 0
	global_load_lds_dwordx4 v[134:135], off
	s_mov_b32 m0, s34
	s_nop 0
	global_load_lds_dwordx4 v[136:137], off
	s_waitcnt vmcnt(8)
	s_waitcnt lgkmcnt(0)
	s_barrier
	s_setprio 1
	v_mfma_f32_16x16x32_bf16 v[30:33], v[82:85], v[98:101], v[30:33]
	v_mfma_f32_16x16x32_bf16 v[26:29], v[90:93], v[98:101], v[26:29]
	v_mfma_f32_16x16x32_bf16 v[22:25], v[82:85], v[106:109], v[22:25]
	v_mfma_f32_16x16x32_bf16 v[18:21], v[90:93], v[106:109], v[18:21]
	v_mfma_f32_16x16x32_bf16 v[14:17], v[82:85], v[114:117], v[14:17]
	v_mfma_f32_16x16x32_bf16 v[10:13], v[90:93], v[114:117], v[10:13]
	v_mfma_f32_16x16x32_bf16 v[6:9], v[82:85], v[122:125], v[6:9]
	v_mfma_f32_16x16x32_bf16 v[2:5], v[90:93], v[122:125], v[2:5]
	v_mfma_f32_16x16x32_bf16 v[30:33], v[86:89], v[102:105], v[30:33]
	v_mfma_f32_16x16x32_bf16 v[26:29], v[94:97], v[102:105], v[26:29]
	v_mfma_f32_16x16x32_bf16 v[22:25], v[86:89], v[110:113], v[22:25]
	v_mfma_f32_16x16x32_bf16 v[18:21], v[94:97], v[110:113], v[18:21]
	v_mfma_f32_16x16x32_bf16 v[14:17], v[86:89], v[118:121], v[14:17]
	v_mfma_f32_16x16x32_bf16 v[10:13], v[94:97], v[118:121], v[10:13]
	v_mfma_f32_16x16x32_bf16 v[6:9], v[86:89], v[126:129], v[6:9]
	v_mfma_f32_16x16x32_bf16 v[2:5], v[94:97], v[126:129], v[2:5]
	s_setprio 0
	s_barrier
	s_add_i32 s53, 0, 0x18000
	v_add_u32_e32 v94, s53, v80
	ds_read_b128 v[82:85], v94
	ds_read_b128 v[86:89], v94 offset:1024
	ds_read_b128 v[90:93], v94 offset:2048
	ds_read_b128 v[94:97], v94 offset:3072
	s_add_u32 s16, s22, 0x28000
	s_addc_u32 s17, s23, 0
	s_mov_b32 m0, s35
	v_lshl_add_u64 v[138:139], s[16:17], 0, v[72:73]
	ds_read_b128 v[98:101], v81 offset:32768
	ds_read_b128 v[102:105], v81 offset:33792
	ds_read_b128 v[106:109], v81 offset:34816
	ds_read_b128 v[110:113], v81 offset:35840
	ds_read_b128 v[114:117], v81 offset:36864
	ds_read_b128 v[118:121], v81 offset:37888
	ds_read_b128 v[122:125], v81 offset:38912
	ds_read_b128 v[126:129], v81 offset:39936
	global_load_lds_dwordx4 v[138:139], off
	v_lshl_add_u64 v[138:139], s[16:17], 0, v[68:69]
	s_mov_b32 m0, s36
	s_nop 0
	global_load_lds_dwordx4 v[138:139], off
	s_waitcnt vmcnt(8)
	s_waitcnt lgkmcnt(0)
	s_barrier
	s_setprio 1
	v_mfma_f32_16x16x32_bf16 v[62:65], v[82:85], v[98:101], v[62:65]
	v_mfma_f32_16x16x32_bf16 v[58:61], v[90:93], v[98:101], v[58:61]
	v_mfma_f32_16x16x32_bf16 v[54:57], v[82:85], v[106:109], v[54:57]
	v_mfma_f32_16x16x32_bf16 v[50:53], v[90:93], v[106:109], v[50:53]
	v_mfma_f32_16x16x32_bf16 v[46:49], v[82:85], v[114:117], v[46:49]
	v_mfma_f32_16x16x32_bf16 v[42:45], v[90:93], v[114:117], v[42:45]
	v_mfma_f32_16x16x32_bf16 v[38:41], v[82:85], v[122:125], v[38:41]
	v_mfma_f32_16x16x32_bf16 v[34:37], v[90:93], v[122:125], v[34:37]
	v_mfma_f32_16x16x32_bf16 v[62:65], v[86:89], v[102:105], v[62:65]
	v_mfma_f32_16x16x32_bf16 v[58:61], v[94:97], v[102:105], v[58:61]
	v_mfma_f32_16x16x32_bf16 v[54:57], v[86:89], v[110:113], v[54:57]
	v_mfma_f32_16x16x32_bf16 v[50:53], v[94:97], v[110:113], v[50:53]
	v_mfma_f32_16x16x32_bf16 v[46:49], v[86:89], v[118:121], v[46:49]
	v_mfma_f32_16x16x32_bf16 v[42:45], v[94:97], v[118:121], v[42:45]
	v_mfma_f32_16x16x32_bf16 v[38:41], v[86:89], v[126:129], v[38:41]
	v_mfma_f32_16x16x32_bf16 v[34:37], v[94:97], v[126:129], v[34:37]
	s_setprio 0
	s_barrier
	s_add_i32 s16, s53, s28
	v_lshl_add_u64 v[130:131], v[130:131], 0, s[54:55]
	s_mov_b32 m0, s16
	ds_read_b128 v[98:101], v81 offset:49152
	ds_read_b128 v[102:105], v81 offset:50176
	ds_read_b128 v[106:109], v81 offset:51200
	ds_read_b128 v[110:113], v81 offset:52224
	ds_read_b128 v[114:117], v81 offset:53248
	ds_read_b128 v[118:121], v81 offset:54272
	ds_read_b128 v[122:125], v81 offset:55296
	ds_read_b128 v[126:129], v81 offset:56320
	global_load_lds_dwordx4 v[130:131], off
	s_add_i32 m0, s16, 0x2000
	s_add_u32 s16, s20, 0x20080
	v_lshl_add_u64 v[130:131], v[132:133], 0, s[54:55]
	s_addc_u32 s17, s21, 0
	global_load_lds_dwordx4 v[130:131], off
	v_lshl_add_u64 v[130:131], s[16:17], 0, v[70:71]
	s_mov_b32 m0, s39
	s_nop 0
	global_load_lds_dwordx4 v[130:131], off
	v_lshl_add_u64 v[130:131], s[16:17], 0, v[66:67]
	s_mov_b32 m0, s40
	s_nop 0
	global_load_lds_dwordx4 v[130:131], off
	v_lshl_add_u64 v[130:131], v[134:135], 0, s[54:55]
	s_mov_b32 m0, s37
	s_nop 0
	global_load_lds_dwordx4 v[130:131], off
	v_lshl_add_u64 v[130:131], v[136:137], 0, s[54:55]
	s_mov_b32 m0, s38
	s_nop 0
	global_load_lds_dwordx4 v[130:131], off
	s_waitcnt vmcnt(8)
	s_waitcnt lgkmcnt(0)
	s_barrier
	s_setprio 1
	v_mfma_f32_16x16x32_bf16 v[30:33], v[82:85], v[98:101], v[30:33]
	v_mfma_f32_16x16x32_bf16 v[26:29], v[90:93], v[98:101], v[26:29]
	v_mfma_f32_16x16x32_bf16 v[22:25], v[82:85], v[106:109], v[22:25]
	v_mfma_f32_16x16x32_bf16 v[18:21], v[90:93], v[106:109], v[18:21]
	v_mfma_f32_16x16x32_bf16 v[14:17], v[82:85], v[114:117], v[14:17]
	v_mfma_f32_16x16x32_bf16 v[10:13], v[90:93], v[114:117], v[10:13]
	v_mfma_f32_16x16x32_bf16 v[6:9], v[82:85], v[122:125], v[6:9]
	v_mfma_f32_16x16x32_bf16 v[2:5], v[90:93], v[122:125], v[2:5]
	v_mfma_f32_16x16x32_bf16 v[30:33], v[86:89], v[102:105], v[30:33]
	v_mfma_f32_16x16x32_bf16 v[26:29], v[94:97], v[102:105], v[26:29]
	v_mfma_f32_16x16x32_bf16 v[22:25], v[86:89], v[110:113], v[22:25]
	v_mfma_f32_16x16x32_bf16 v[18:21], v[94:97], v[110:113], v[18:21]
	v_mfma_f32_16x16x32_bf16 v[14:17], v[86:89], v[118:121], v[14:17]
	v_mfma_f32_16x16x32_bf16 v[10:13], v[94:97], v[118:121], v[10:13]
	v_mfma_f32_16x16x32_bf16 v[6:9], v[86:89], v[126:129], v[6:9]
	v_mfma_f32_16x16x32_bf16 v[2:5], v[94:97], v[126:129], v[2:5]
	s_setprio 0
	s_barrier
	s_add_i32 s52, s52, 2
	s_add_u32 s46, s46, 0x100
	s_addc_u32 s47, s47, 0
	s_cmp_gt_u32 s52, 5
	s_mov_b64 s[16:17], s[18:19]
	s_cbranch_scc0 .LBB0_245
	s_and_b64 vcc, exec, s[6:7]
	s_cbranch_vccz .LBB0_248
	s_barrier

.LBB0_407:
	s_add_u32 s18, s16, 0x100
	s_addc_u32 s19, s17, 0
	s_add_i32 s47, 0, 0x10000
	s_cmp_eq_u32 s46, 6
	s_cselect_b32 s23, s13, s19
	s_cselect_b32 s22, s12, s18
	v_add_u32_e32 v0, s47, v201
	s_cselect_b32 s21, s15, s45
	s_cselect_b32 s20, s14, s3
	s_add_i32 s50, 0, 0x14000
	ds_read_b128 v[34:37], v0
	ds_read_b128 v[38:41], v0 offset:1024
	ds_read_b128 v[106:109], v0 offset:2048
	ds_read_b128 v[118:121], v0 offset:3072
	v_add_u32_e32 v0, s50, v201
	ds_read_b128 v[130:133], v0
	ds_read_b128 v[142:145], v0 offset:1024
	ds_read_b128 v[146:149], v0 offset:2048
	ds_read_b128 v[154:157], v0 offset:3072
	v_lshl_add_u64 v[198:199], s[16:17], 0, v[192:193]
	s_add_i32 m0, s31, 0xc000
	ds_read_b128 v[162:165], v204
	ds_read_b128 v[166:169], v204 offset:1024
	ds_read_b128 v[206:209], v204 offset:2048
	ds_read_b128 v[210:213], v204 offset:3072
	ds_read_b128 v[214:217], v204 offset:4096
	ds_read_b128 v[236:239], v204 offset:5120
	ds_read_b128 v[240:243], v204 offset:6144
	ds_read_b128 v[244:247], v204 offset:7168
	global_load_lds_dwordx4 v[198:199], off
	v_lshl_add_u64 v[198:199], s[16:17], 0, v[194:195]
	s_add_i32 m0, s31, 0xe000
	s_nop 0
	global_load_lds_dwordx4 v[198:199], off
	s_waitcnt vmcnt(8)
	s_waitcnt lgkmcnt(0)
	s_barrier
	s_setprio 1
	v_mfma_f32_16x16x32_bf16 v[158:161], v[34:37], v[162:165], v[158:161]
	v_mfma_f32_16x16x32_bf16 v[150:153], v[106:109], v[162:165], v[150:153]
	v_mfma_f32_16x16x32_bf16 v[126:129], v[34:37], v[206:209], v[126:129]
	v_mfma_f32_16x16x32_bf16 v[122:125], v[106:109], v[206:209], v[122:125]
	v_mfma_f32_16x16x32_bf16 v[102:105], v[34:37], v[214:217], v[102:105]
	v_mfma_f32_16x16x32_bf16 v[98:101], v[106:109], v[214:217], v[98:101]
	v_mfma_f32_16x16x32_bf16 v[86:89], v[34:37], v[240:243], v[86:89]
	v_mfma_f32_16x16x32_bf16 v[82:85], v[106:109], v[240:243], v[82:85]
	v_mfma_f32_16x16x32_bf16 v[158:161], v[38:41], v[166:169], v[158:161]
	v_mfma_f32_16x16x32_bf16 v[150:153], v[118:121], v[166:169], v[150:153]
	v_mfma_f32_16x16x32_bf16 v[126:129], v[38:41], v[210:213], v[126:129]
	v_mfma_f32_16x16x32_bf16 v[122:125], v[118:121], v[210:213], v[122:125]
	v_mfma_f32_16x16x32_bf16 v[102:105], v[38:41], v[236:239], v[102:105]
	v_mfma_f32_16x16x32_bf16 v[98:101], v[118:121], v[236:239], v[98:101]
	v_mfma_f32_16x16x32_bf16 v[86:89], v[38:41], v[244:247], v[86:89]
	v_mfma_f32_16x16x32_bf16 v[82:85], v[118:121], v[244:247], v[82:85]
	v_mfma_f32_16x16x32_bf16 v[138:141], v[130:133], v[162:165], v[138:141]
	v_mfma_f32_16x16x32_bf16 v[134:137], v[146:149], v[162:165], v[134:137]
	v_mfma_f32_16x16x32_bf16 v[114:117], v[130:133], v[206:209], v[114:117]
	v_mfma_f32_16x16x32_bf16 v[110:113], v[146:149], v[206:209], v[110:113]
	v_mfma_f32_16x16x32_bf16 v[94:97], v[130:133], v[214:217], v[94:97]
	v_mfma_f32_16x16x32_bf16 v[90:93], v[146:149], v[214:217], v[90:93]
	v_mfma_f32_16x16x32_bf16 v[78:81], v[130:133], v[240:243], v[78:81]
	v_mfma_f32_16x16x32_bf16 v[74:77], v[146:149], v[240:243], v[74:77]
	v_mfma_f32_16x16x32_bf16 v[138:141], v[142:145], v[166:169], v[138:141]
	v_mfma_f32_16x16x32_bf16 v[134:137], v[154:157], v[166:169], v[134:137]
	v_mfma_f32_16x16x32_bf16 v[114:117], v[142:145], v[210:213], v[114:117]
	v_mfma_f32_16x16x32_bf16 v[110:113], v[154:157], v[210:213], v[110:113]
	v_mfma_f32_16x16x32_bf16 v[94:97], v[142:145], v[236:239], v[94:97]
	v_mfma_f32_16x16x32_bf16 v[90:93], v[154:157], v[236:239], v[90:93]
	v_mfma_f32_16x16x32_bf16 v[78:81], v[142:145], v[244:247], v[78:81]
	v_mfma_f32_16x16x32_bf16 v[74:77], v[154:157], v[244:247], v[74:77]
	s_setprio 0
	s_barrier
	s_add_i32 s16, s47, s30
	v_lshl_add_u64 v[198:199], s[20:21], 0, v[184:185]
	s_mov_b32 m0, s16
	ds_read_b128 v[162:165], v204 offset:16384
	ds_read_b128 v[166:169], v204 offset:17408
	ds_read_b128 v[206:209], v204 offset:18432
	ds_read_b128 v[210:213], v204 offset:19456
	ds_read_b128 v[214:217], v204 offset:20480
	ds_read_b128 v[236:239], v204 offset:21504
	ds_read_b128 v[240:243], v204 offset:22528
	ds_read_b128 v[244:247], v204 offset:23552
	global_load_lds_dwordx4 v[198:199], off
	s_add_i32 m0, s16, 0x2000
	s_add_u32 s16, s20, 0x28000
	v_lshl_add_u64 v[218:219], s[20:21], 0, v[180:181]
	s_addc_u32 s17, s21, 0
	s_add_i32 s47, s50, s30
	global_load_lds_dwordx4 v[218:219], off
	v_lshl_add_u64 v[222:223], s[16:17], 0, v[184:185]
	s_mov_b32 m0, s47
	v_lshl_add_u64 v[232:233], s[22:23], 0, v[182:183]
	global_load_lds_dwordx4 v[222:223], off
	v_lshl_add_u64 v[222:223], s[16:17], 0, v[180:181]
	s_add_i32 m0, s47, 0x2000
	s_nop 0
	global_load_lds_dwordx4 v[222:223], off
	v_lshl_add_u64 v[222:223], s[22:23], 0, v[186:187]
	s_mov_b32 m0, s31
	s_nop 0
	global_load_lds_dwordx4 v[222:223], off
	s_mov_b32 m0, s34
	s_nop 0
	global_load_lds_dwordx4 v[232:233], off
	s_waitcnt vmcnt(8)
	s_waitcnt lgkmcnt(0)
	s_barrier
	s_setprio 1
	v_mfma_f32_16x16x32_bf16 v[70:73], v[34:37], v[162:165], v[70:73]
	v_mfma_f32_16x16x32_bf16 v[66:69], v[106:109], v[162:165], v[66:69]
	v_mfma_f32_16x16x32_bf16 v[54:57], v[34:37], v[206:209], v[54:57]
	v_mfma_f32_16x16x32_bf16 v[50:53], v[106:109], v[206:209], v[50:53]
	v_mfma_f32_16x16x32_bf16 v[30:33], v[34:37], v[214:217], v[30:33]
	v_mfma_f32_16x16x32_bf16 v[26:29], v[106:109], v[214:217], v[26:29]
	v_mfma_f32_16x16x32_bf16 v[14:17], v[34:37], v[240:243], v[14:17]
	v_mfma_f32_16x16x32_bf16 v[10:13], v[106:109], v[240:243], v[10:13]
	v_mfma_f32_16x16x32_bf16 v[70:73], v[38:41], v[166:169], v[70:73]
	v_mfma_f32_16x16x32_bf16 v[66:69], v[118:121], v[166:169], v[66:69]
	v_mfma_f32_16x16x32_bf16 v[54:57], v[38:41], v[210:213], v[54:57]
	v_mfma_f32_16x16x32_bf16 v[50:53], v[118:121], v[210:213], v[50:53]
	v_mfma_f32_16x16x32_bf16 v[30:33], v[38:41], v[236:239], v[30:33]
	v_mfma_f32_16x16x32_bf16 v[26:29], v[118:121], v[236:239], v[26:29]
	v_mfma_f32_16x16x32_bf16 v[14:17], v[38:41], v[244:247], v[14:17]
	v_mfma_f32_16x16x32_bf16 v[10:13], v[118:121], v[244:247], v[10:13]
	v_mfma_f32_16x16x32_bf16 v[46:49], v[130:133], v[206:209], v[46:49]
	v_mfma_f32_16x16x32_bf16 v[42:45], v[146:149], v[206:209], v[42:45]
	v_mfma_f32_16x16x32_bf16 v[22:25], v[130:133], v[214:217], v[22:25]
	v_mfma_f32_16x16x32_bf16 v[18:21], v[146:149], v[214:217], v[18:21]
	v_mfma_f32_16x16x32_bf16 v[6:9], v[130:133], v[240:243], v[6:9]
	v_mfma_f32_16x16x32_bf16 v[2:5], v[146:149], v[240:243], v[2:5]
	v_mfma_f32_16x16x32_bf16 v[34:37], v[130:133], v[162:165], v[62:65]
	v_mfma_f32_16x16x32_bf16 v[38:41], v[146:149], v[162:165], v[58:61]
	v_mfma_f32_16x16x32_bf16 v[46:49], v[142:145], v[210:213], v[46:49]
	v_mfma_f32_16x16x32_bf16 v[42:45], v[154:157], v[210:213], v[42:45]
	v_mfma_f32_16x16x32_bf16 v[22:25], v[142:145], v[236:239], v[22:25]
	v_mfma_f32_16x16x32_bf16 v[18:21], v[154:157], v[236:239], v[18:21]
	v_mfma_f32_16x16x32_bf16 v[6:9], v[142:145], v[244:247], v[6:9]
	v_mfma_f32_16x16x32_bf16 v[2:5], v[154:157], v[244:247], v[2:5]
	v_mfma_f32_16x16x32_bf16 v[34:37], v[142:145], v[166:169], v[34:37]
	v_mfma_f32_16x16x32_bf16 v[38:41], v[154:157], v[166:169], v[38:41]
	s_setprio 0
	s_barrier
	s_add_i32 s47, 0, 0x18000
	v_add_u32_e32 v0, s47, v201
	s_add_i32 s50, 0, 0x1c000
	ds_read_b128 v[58:61], v0
	ds_read_b128 v[62:65], v0 offset:1024
	ds_read_b128 v[106:109], v0 offset:2048
	ds_read_b128 v[118:121], v0 offset:3072
	v_add_u32_e32 v0, s50, v201
	ds_read_b128 v[130:133], v0
	ds_read_b128 v[142:145], v0 offset:1024
	ds_read_b128 v[146:149], v0 offset:2048
	ds_read_b128 v[154:157], v0 offset:3072
	s_add_u32 s16, s22, 0x28000
	s_addc_u32 s17, s23, 0
	s_mov_b32 m0, s35
	v_lshl_add_u64 v[248:249], s[16:17], 0, v[186:187]
	ds_read_b128 v[162:165], v204 offset:32768
	ds_read_b128 v[166:169], v204 offset:33792
	ds_read_b128 v[206:209], v204 offset:34816
	ds_read_b128 v[210:213], v204 offset:35840
	ds_read_b128 v[214:217], v204 offset:36864
	ds_read_b128 v[236:239], v204 offset:37888
	ds_read_b128 v[240:243], v204 offset:38912
	ds_read_b128 v[244:247], v204 offset:39936
	global_load_lds_dwordx4 v[248:249], off
	v_lshl_add_u64 v[248:249], s[16:17], 0, v[182:183]
	s_mov_b32 m0, s36
	s_nop 0
	global_load_lds_dwordx4 v[248:249], off
	s_waitcnt vmcnt(8)
	s_waitcnt lgkmcnt(0)
	s_barrier
	s_setprio 1
	v_mfma_f32_16x16x32_bf16 v[158:161], v[58:61], v[162:165], v[158:161]
	v_mfma_f32_16x16x32_bf16 v[150:153], v[106:109], v[162:165], v[150:153]
	v_mfma_f32_16x16x32_bf16 v[126:129], v[58:61], v[206:209], v[126:129]
	v_mfma_f32_16x16x32_bf16 v[122:125], v[106:109], v[206:209], v[122:125]
	v_mfma_f32_16x16x32_bf16 v[102:105], v[58:61], v[214:217], v[102:105]
	v_mfma_f32_16x16x32_bf16 v[98:101], v[106:109], v[214:217], v[98:101]
	v_mfma_f32_16x16x32_bf16 v[86:89], v[58:61], v[240:243], v[86:89]
	v_mfma_f32_16x16x32_bf16 v[82:85], v[106:109], v[240:243], v[82:85]
	v_mfma_f32_16x16x32_bf16 v[158:161], v[62:65], v[166:169], v[158:161]
	v_mfma_f32_16x16x32_bf16 v[150:153], v[118:121], v[166:169], v[150:153]
	v_mfma_f32_16x16x32_bf16 v[126:129], v[62:65], v[210:213], v[126:129]
	v_mfma_f32_16x16x32_bf16 v[122:125], v[118:121], v[210:213], v[122:125]
	v_mfma_f32_16x16x32_bf16 v[102:105], v[62:65], v[236:239], v[102:105]
	v_mfma_f32_16x16x32_bf16 v[98:101], v[118:121], v[236:239], v[98:101]
	v_mfma_f32_16x16x32_bf16 v[86:89], v[62:65], v[244:247], v[86:89]
	v_mfma_f32_16x16x32_bf16 v[82:85], v[118:121], v[244:247], v[82:85]
	v_mfma_f32_16x16x32_bf16 v[138:141], v[130:133], v[162:165], v[138:141]
	v_mfma_f32_16x16x32_bf16 v[134:137], v[146:149], v[162:165], v[134:137]
	v_mfma_f32_16x16x32_bf16 v[114:117], v[130:133], v[206:209], v[114:117]
	v_mfma_f32_16x16x32_bf16 v[110:113], v[146:149], v[206:209], v[110:113]
	v_mfma_f32_16x16x32_bf16 v[94:97], v[130:133], v[214:217], v[94:97]
	v_mfma_f32_16x16x32_bf16 v[90:93], v[146:149], v[214:217], v[90:93]
	v_mfma_f32_16x16x32_bf16 v[78:81], v[130:133], v[240:243], v[78:81]
	v_mfma_f32_16x16x32_bf16 v[74:77], v[146:149], v[240:243], v[74:77]
	v_mfma_f32_16x16x32_bf16 v[138:141], v[142:145], v[166:169], v[138:141]
	v_mfma_f32_16x16x32_bf16 v[134:137], v[154:157], v[166:169], v[134:137]
	v_mfma_f32_16x16x32_bf16 v[114:117], v[142:145], v[210:213], v[114:117]
	v_mfma_f32_16x16x32_bf16 v[110:113], v[154:157], v[210:213], v[110:113]
	v_mfma_f32_16x16x32_bf16 v[94:97], v[142:145], v[236:239], v[94:97]
	v_mfma_f32_16x16x32_bf16 v[90:93], v[154:157], v[236:239], v[90:93]
	v_mfma_f32_16x16x32_bf16 v[78:81], v[142:145], v[244:247], v[78:81]
	v_mfma_f32_16x16x32_bf16 v[74:77], v[154:157], v[244:247], v[74:77]
	s_setprio 0
	s_barrier
	s_add_i32 s16, s47, s30
	v_lshl_add_u64 v[198:199], v[198:199], 0, s[54:55]
	s_mov_b32 m0, s16
	ds_read_b128 v[162:165], v204 offset:49152
	ds_read_b128 v[166:169], v204 offset:50176
	ds_read_b128 v[206:209], v204 offset:51200
	ds_read_b128 v[210:213], v204 offset:52224
	ds_read_b128 v[214:217], v204 offset:53248
	ds_read_b128 v[236:239], v204 offset:54272
	ds_read_b128 v[240:243], v204 offset:55296
	ds_read_b128 v[244:247], v204 offset:56320
	global_load_lds_dwordx4 v[198:199], off
	s_add_i32 m0, s16, 0x2000
	s_add_u32 s16, s20, 0x28080
	v_lshl_add_u64 v[198:199], v[218:219], 0, s[54:55]
	s_addc_u32 s17, s21, 0
	s_add_i32 s20, s50, s30
	global_load_lds_dwordx4 v[198:199], off
	v_lshl_add_u64 v[198:199], s[16:17], 0, v[184:185]
	s_mov_b32 m0, s20
	s_nop 0
	global_load_lds_dwordx4 v[198:199], off
	v_lshl_add_u64 v[198:199], s[16:17], 0, v[180:181]
	s_add_i32 m0, s20, 0x2000
	s_nop 0
	global_load_lds_dwordx4 v[198:199], off
	v_lshl_add_u64 v[198:199], v[222:223], 0, s[54:55]
	s_mov_b32 m0, s38
	s_nop 0
	global_load_lds_dwordx4 v[198:199], off
	v_lshl_add_u64 v[198:199], v[232:233], 0, s[54:55]
	s_mov_b32 m0, s39
	s_nop 0
	global_load_lds_dwordx4 v[198:199], off
	s_waitcnt vmcnt(8)
	s_waitcnt lgkmcnt(0)
	s_barrier
	s_setprio 1
	v_mfma_f32_16x16x32_bf16 v[70:73], v[58:61], v[162:165], v[70:73]
	v_mfma_f32_16x16x32_bf16 v[66:69], v[106:109], v[162:165], v[66:69]
	v_mfma_f32_16x16x32_bf16 v[54:57], v[58:61], v[206:209], v[54:57]
	v_mfma_f32_16x16x32_bf16 v[50:53], v[106:109], v[206:209], v[50:53]
	v_mfma_f32_16x16x32_bf16 v[30:33], v[58:61], v[214:217], v[30:33]
	v_mfma_f32_16x16x32_bf16 v[26:29], v[106:109], v[214:217], v[26:29]
	v_mfma_f32_16x16x32_bf16 v[14:17], v[58:61], v[240:243], v[14:17]
	v_mfma_f32_16x16x32_bf16 v[10:13], v[106:109], v[240:243], v[10:13]
	v_mfma_f32_16x16x32_bf16 v[70:73], v[62:65], v[166:169], v[70:73]
	v_mfma_f32_16x16x32_bf16 v[66:69], v[118:121], v[166:169], v[66:69]
	v_mfma_f32_16x16x32_bf16 v[54:57], v[62:65], v[210:213], v[54:57]
	v_mfma_f32_16x16x32_bf16 v[50:53], v[118:121], v[210:213], v[50:53]
	v_mfma_f32_16x16x32_bf16 v[30:33], v[62:65], v[236:239], v[30:33]
	v_mfma_f32_16x16x32_bf16 v[26:29], v[118:121], v[236:239], v[26:29]
	v_mfma_f32_16x16x32_bf16 v[14:17], v[62:65], v[244:247], v[14:17]
	v_mfma_f32_16x16x32_bf16 v[10:13], v[118:121], v[244:247], v[10:13]
	v_mfma_f32_16x16x32_bf16 v[34:37], v[130:133], v[162:165], v[34:37]
	v_mfma_f32_16x16x32_bf16 v[62:65], v[142:145], v[166:169], v[34:37]
	v_mfma_f32_16x16x32_bf16 v[34:37], v[146:149], v[162:165], v[38:41]
	v_mfma_f32_16x16x32_bf16 v[58:61], v[154:157], v[166:169], v[34:37]
	v_mfma_f32_16x16x32_bf16 v[34:37], v[130:133], v[206:209], v[46:49]
	v_mfma_f32_16x16x32_bf16 v[46:49], v[142:145], v[210:213], v[34:37]
	v_mfma_f32_16x16x32_bf16 v[34:37], v[146:149], v[206:209], v[42:45]
	v_mfma_f32_16x16x32_bf16 v[22:25], v[130:133], v[214:217], v[22:25]
	v_mfma_f32_16x16x32_bf16 v[18:21], v[146:149], v[214:217], v[18:21]
	v_mfma_f32_16x16x32_bf16 v[6:9], v[130:133], v[240:243], v[6:9]
	v_mfma_f32_16x16x32_bf16 v[2:5], v[146:149], v[240:243], v[2:5]
	v_mfma_f32_16x16x32_bf16 v[42:45], v[154:157], v[210:213], v[34:37]
	v_mfma_f32_16x16x32_bf16 v[22:25], v[142:145], v[236:239], v[22:25]
	v_mfma_f32_16x16x32_bf16 v[18:21], v[154:157], v[236:239], v[18:21]
	v_mfma_f32_16x16x32_bf16 v[6:9], v[142:145], v[244:247], v[6:9]
	v_mfma_f32_16x16x32_bf16 v[2:5], v[154:157], v[244:247], v[2:5]
	s_setprio 0
	s_barrier
	s_add_i32 s46, s46, 2
	s_add_u32 s3, s3, 0x100
	s_addc_u32 s45, s45, 0
	s_cmp_gt_u32 s46, 7
	s_mov_b64 s[16:17], s[18:19]
	s_cbranch_scc0 .LBB0_407
	s_and_b64 vcc, exec, s[10:11]
	s_cbranch_vccz .LBB0_410
	s_barrier

.LBB0_501:
	s_add_u32 s30, s28, 0xfffc0080
	s_addc_u32 s31, s29, -1
	s_add_i32 s53, 0, 0x10000
	s_cmp_eq_u32 s50, 12
	s_cselect_b32 s35, s2, s31
	s_cselect_b32 s34, s3, s30
	s_cselect_b32 s31, s17, s27
	s_cselect_b32 s30, s19, s25
	s_add_i32 s60, 0, 0x14000
	v_add_u32_e32 v142, s53, v236
	v_add_u32_e32 v158, s60, v236
	ds_read_b128 v[114:117], v142
	ds_read_b128 v[122:125], v142 offset:1024
	ds_read_b128 v[130:133], v142 offset:2048
	ds_read_b128 v[142:145], v142 offset:3072
	ds_read_b128 v[146:149], v158
	ds_read_b128 v[150:153], v158 offset:1024
	ds_read_b128 v[154:157], v158 offset:2048
	ds_read_b128 v[158:161], v158 offset:3072
	v_lshl_add_u64 v[216:217], s[28:29], 0, v[180:181]
	s_add_i32 m0, s43, 0xc000
	ds_read_b128 v[184:187], v238
	ds_read_b128 v[188:191], v238 offset:1024
	ds_read_b128 v[192:195], v238 offset:2048
	ds_read_b128 v[196:199], v238 offset:3072
	ds_read_b128 v[200:203], v238 offset:4096
	ds_read_b128 v[204:207], v238 offset:5120
	ds_read_b128 v[208:211], v238 offset:6144
	ds_read_b128 v[212:215], v238 offset:7168
	global_load_lds_dwordx4 v[216:217], off
	v_lshl_add_u64 v[216:217], s[28:29], 0, v[182:183]
	s_add_i32 m0, s43, 0xe000
	s_nop 0
	global_load_lds_dwordx4 v[216:217], off
	s_waitcnt vmcnt(8)
	s_waitcnt lgkmcnt(0)
	s_barrier
	s_setprio 1
	v_mfma_f32_16x16x32_bf16 v[138:141], v[114:117], v[184:187], v[138:141]
	v_mfma_f32_16x16x32_bf16 v[118:121], v[130:133], v[184:187], v[118:121]
	v_mfma_f32_16x16x32_bf16 v[110:113], v[114:117], v[192:195], v[110:113]
	v_mfma_f32_16x16x32_bf16 v[102:105], v[130:133], v[192:195], v[102:105]
	v_mfma_f32_16x16x32_bf16 v[94:97], v[114:117], v[200:203], v[94:97]
	v_mfma_f32_16x16x32_bf16 v[86:89], v[130:133], v[200:203], v[86:89]
	v_mfma_f32_16x16x32_bf16 v[78:81], v[114:117], v[208:211], v[78:81]
	v_mfma_f32_16x16x32_bf16 v[70:73], v[130:133], v[208:211], v[70:73]
	v_mfma_f32_16x16x32_bf16 v[138:141], v[122:125], v[188:191], v[138:141]
	v_mfma_f32_16x16x32_bf16 v[118:121], v[142:145], v[188:191], v[118:121]
	v_mfma_f32_16x16x32_bf16 v[110:113], v[122:125], v[196:199], v[110:113]
	v_mfma_f32_16x16x32_bf16 v[102:105], v[142:145], v[196:199], v[102:105]
	v_mfma_f32_16x16x32_bf16 v[94:97], v[122:125], v[204:207], v[94:97]
	v_mfma_f32_16x16x32_bf16 v[86:89], v[142:145], v[204:207], v[86:89]
	v_mfma_f32_16x16x32_bf16 v[78:81], v[122:125], v[212:215], v[78:81]
	v_mfma_f32_16x16x32_bf16 v[70:73], v[142:145], v[212:215], v[70:73]
	v_mfma_f32_16x16x32_bf16 v[134:137], v[146:149], v[184:187], v[134:137]
	v_mfma_f32_16x16x32_bf16 v[126:129], v[154:157], v[184:187], v[126:129]
	v_mfma_f32_16x16x32_bf16 v[106:109], v[146:149], v[192:195], v[106:109]
	v_mfma_f32_16x16x32_bf16 v[98:101], v[154:157], v[192:195], v[98:101]
	v_mfma_f32_16x16x32_bf16 v[90:93], v[146:149], v[200:203], v[90:93]
	v_mfma_f32_16x16x32_bf16 v[82:85], v[154:157], v[200:203], v[82:85]
	v_mfma_f32_16x16x32_bf16 v[74:77], v[146:149], v[208:211], v[74:77]
	v_mfma_f32_16x16x32_bf16 v[66:69], v[154:157], v[208:211], v[66:69]
	v_mfma_f32_16x16x32_bf16 v[134:137], v[150:153], v[188:191], v[134:137]
	v_mfma_f32_16x16x32_bf16 v[126:129], v[158:161], v[188:191], v[126:129]
	v_mfma_f32_16x16x32_bf16 v[106:109], v[150:153], v[196:199], v[106:109]
	v_mfma_f32_16x16x32_bf16 v[98:101], v[158:161], v[196:199], v[98:101]
	v_mfma_f32_16x16x32_bf16 v[90:93], v[150:153], v[204:207], v[90:93]
	v_mfma_f32_16x16x32_bf16 v[82:85], v[158:161], v[204:207], v[82:85]
	v_mfma_f32_16x16x32_bf16 v[74:77], v[150:153], v[212:215], v[74:77]
	v_mfma_f32_16x16x32_bf16 v[66:69], v[158:161], v[212:215], v[66:69]
	s_setprio 0
	s_barrier
	s_add_i32 s53, s53, s42
	v_lshl_add_u64 v[216:217], s[30:31], 0, v[0:1]
	s_mov_b32 m0, s53
	ds_read_b128 v[184:187], v238 offset:16384
	ds_read_b128 v[188:191], v238 offset:17408
	ds_read_b128 v[192:195], v238 offset:18432
	ds_read_b128 v[196:199], v238 offset:19456
	ds_read_b128 v[200:203], v238 offset:20480
	ds_read_b128 v[204:207], v238 offset:21504
	ds_read_b128 v[208:211], v238 offset:22528
	ds_read_b128 v[212:215], v238 offset:23552
	global_load_lds_dwordx4 v[216:217], off
	s_add_i32 m0, s53, 0x2000
	s_add_u32 s64, s30, 0x40000
	v_lshl_add_u64 v[218:219], s[30:31], 0, v[166:167]
	s_addc_u32 s65, s31, 0
	s_add_i32 s53, s60, s42
	global_load_lds_dwordx4 v[218:219], off
	v_lshl_add_u64 v[222:223], s[64:65], 0, v[0:1]
	s_mov_b32 m0, s53
	v_lshl_add_u64 v[232:233], s[34:35], 0, v[164:165]
	global_load_lds_dwordx4 v[222:223], off
	v_lshl_add_u64 v[222:223], s[64:65], 0, v[166:167]
	s_add_i32 m0, s53, 0x2000
	s_nop 0
	global_load_lds_dwordx4 v[222:223], off
	v_lshl_add_u64 v[222:223], s[34:35], 0, v[162:163]
	s_mov_b32 m0, s43
	s_nop 0
	global_load_lds_dwordx4 v[222:223], off
	s_mov_b32 m0, s45
	s_nop 0
	global_load_lds_dwordx4 v[232:233], off
	s_waitcnt vmcnt(8)
	s_waitcnt lgkmcnt(0)
	s_barrier
	s_setprio 1
	v_mfma_f32_16x16x32_bf16 v[62:65], v[114:117], v[184:187], v[62:65]
	v_mfma_f32_16x16x32_bf16 v[54:57], v[130:133], v[184:187], v[54:57]
	v_mfma_f32_16x16x32_bf16 v[46:49], v[114:117], v[192:195], v[46:49]
	v_mfma_f32_16x16x32_bf16 v[38:41], v[130:133], v[192:195], v[38:41]
	v_mfma_f32_16x16x32_bf16 v[30:33], v[114:117], v[200:203], v[30:33]
	v_mfma_f32_16x16x32_bf16 v[22:25], v[130:133], v[200:203], v[22:25]
	v_mfma_f32_16x16x32_bf16 v[14:17], v[114:117], v[208:211], v[14:17]
	v_mfma_f32_16x16x32_bf16 v[6:9], v[130:133], v[208:211], v[6:9]
	v_mfma_f32_16x16x32_bf16 v[62:65], v[122:125], v[188:191], v[62:65]
	v_mfma_f32_16x16x32_bf16 v[54:57], v[142:145], v[188:191], v[54:57]
	v_mfma_f32_16x16x32_bf16 v[46:49], v[122:125], v[196:199], v[46:49]
	v_mfma_f32_16x16x32_bf16 v[38:41], v[142:145], v[196:199], v[38:41]
	v_mfma_f32_16x16x32_bf16 v[30:33], v[122:125], v[204:207], v[30:33]
	v_mfma_f32_16x16x32_bf16 v[22:25], v[142:145], v[204:207], v[22:25]
	v_mfma_f32_16x16x32_bf16 v[14:17], v[122:125], v[212:215], v[14:17]
	v_mfma_f32_16x16x32_bf16 v[6:9], v[142:145], v[212:215], v[6:9]
	v_mfma_f32_16x16x32_bf16 v[58:61], v[146:149], v[184:187], v[58:61]
	v_mfma_f32_16x16x32_bf16 v[50:53], v[154:157], v[184:187], v[50:53]
	v_mfma_f32_16x16x32_bf16 v[42:45], v[146:149], v[192:195], v[42:45]
	v_mfma_f32_16x16x32_bf16 v[34:37], v[154:157], v[192:195], v[34:37]
	v_mfma_f32_16x16x32_bf16 v[26:29], v[146:149], v[200:203], v[26:29]
	v_mfma_f32_16x16x32_bf16 v[18:21], v[154:157], v[200:203], v[18:21]
	v_mfma_f32_16x16x32_bf16 v[10:13], v[146:149], v[208:211], v[10:13]
	v_mfma_f32_16x16x32_bf16 v[2:5], v[154:157], v[208:211], v[2:5]
	v_mfma_f32_16x16x32_bf16 v[58:61], v[150:153], v[188:191], v[58:61]
	v_mfma_f32_16x16x32_bf16 v[50:53], v[158:161], v[188:191], v[50:53]
	v_mfma_f32_16x16x32_bf16 v[42:45], v[150:153], v[196:199], v[42:45]
	v_mfma_f32_16x16x32_bf16 v[34:37], v[158:161], v[196:199], v[34:37]
	v_mfma_f32_16x16x32_bf16 v[26:29], v[150:153], v[204:207], v[26:29]
	v_mfma_f32_16x16x32_bf16 v[18:21], v[158:161], v[204:207], v[18:21]
	v_mfma_f32_16x16x32_bf16 v[10:13], v[150:153], v[212:215], v[10:13]
	v_mfma_f32_16x16x32_bf16 v[2:5], v[158:161], v[212:215], v[2:5]
	s_setprio 0
	s_barrier
	s_add_i32 s53, 0, 0x18000
	s_add_i32 s60, 0, 0x1c000
	v_add_u32_e32 v142, s53, v236
	v_add_u32_e32 v158, s60, v236
	ds_read_b128 v[114:117], v142
	ds_read_b128 v[122:125], v142 offset:1024
	ds_read_b128 v[130:133], v142 offset:2048
	ds_read_b128 v[142:145], v142 offset:3072
	ds_read_b128 v[146:149], v158
	ds_read_b128 v[150:153], v158 offset:1024
	ds_read_b128 v[154:157], v158 offset:2048
	ds_read_b128 v[158:161], v158 offset:3072
	s_add_u32 s34, s34, 0x40000
	s_addc_u32 s35, s35, 0
	s_mov_b32 m0, s46
	v_lshl_add_u64 v[240:241], s[34:35], 0, v[162:163]
	ds_read_b128 v[184:187], v238 offset:32768
	ds_read_b128 v[188:191], v238 offset:33792
	ds_read_b128 v[192:195], v238 offset:34816
	ds_read_b128 v[196:199], v238 offset:35840
	ds_read_b128 v[200:203], v238 offset:36864
	ds_read_b128 v[204:207], v238 offset:37888
	ds_read_b128 v[208:211], v238 offset:38912
	ds_read_b128 v[212:215], v238 offset:39936
	global_load_lds_dwordx4 v[240:241], off
	v_lshl_add_u64 v[240:241], s[34:35], 0, v[164:165]
	s_mov_b32 m0, s47
	s_nop 0
	global_load_lds_dwordx4 v[240:241], off
	s_waitcnt vmcnt(8)
	s_waitcnt lgkmcnt(0)
	s_barrier
	s_setprio 1
	v_mfma_f32_16x16x32_bf16 v[138:141], v[114:117], v[184:187], v[138:141]
	v_mfma_f32_16x16x32_bf16 v[118:121], v[130:133], v[184:187], v[118:121]
	v_mfma_f32_16x16x32_bf16 v[110:113], v[114:117], v[192:195], v[110:113]
	v_mfma_f32_16x16x32_bf16 v[102:105], v[130:133], v[192:195], v[102:105]
	v_mfma_f32_16x16x32_bf16 v[94:97], v[114:117], v[200:203], v[94:97]
	v_mfma_f32_16x16x32_bf16 v[86:89], v[130:133], v[200:203], v[86:89]
	v_mfma_f32_16x16x32_bf16 v[78:81], v[114:117], v[208:211], v[78:81]
	v_mfma_f32_16x16x32_bf16 v[70:73], v[130:133], v[208:211], v[70:73]
	v_mfma_f32_16x16x32_bf16 v[138:141], v[122:125], v[188:191], v[138:141]
	v_mfma_f32_16x16x32_bf16 v[118:121], v[142:145], v[188:191], v[118:121]
	v_mfma_f32_16x16x32_bf16 v[110:113], v[122:125], v[196:199], v[110:113]
	v_mfma_f32_16x16x32_bf16 v[102:105], v[142:145], v[196:199], v[102:105]
	v_mfma_f32_16x16x32_bf16 v[94:97], v[122:125], v[204:207], v[94:97]
	v_mfma_f32_16x16x32_bf16 v[86:89], v[142:145], v[204:207], v[86:89]
	v_mfma_f32_16x16x32_bf16 v[78:81], v[122:125], v[212:215], v[78:81]
	v_mfma_f32_16x16x32_bf16 v[70:73], v[142:145], v[212:215], v[70:73]
	v_mfma_f32_16x16x32_bf16 v[134:137], v[146:149], v[184:187], v[134:137]
	v_mfma_f32_16x16x32_bf16 v[126:129], v[154:157], v[184:187], v[126:129]
	v_mfma_f32_16x16x32_bf16 v[106:109], v[146:149], v[192:195], v[106:109]
	v_mfma_f32_16x16x32_bf16 v[98:101], v[154:157], v[192:195], v[98:101]
	v_mfma_f32_16x16x32_bf16 v[90:93], v[146:149], v[200:203], v[90:93]
	v_mfma_f32_16x16x32_bf16 v[82:85], v[154:157], v[200:203], v[82:85]
	v_mfma_f32_16x16x32_bf16 v[74:77], v[146:149], v[208:211], v[74:77]
	v_mfma_f32_16x16x32_bf16 v[66:69], v[154:157], v[208:211], v[66:69]
	v_mfma_f32_16x16x32_bf16 v[134:137], v[150:153], v[188:191], v[134:137]
	v_mfma_f32_16x16x32_bf16 v[126:129], v[158:161], v[188:191], v[126:129]
	v_mfma_f32_16x16x32_bf16 v[106:109], v[150:153], v[196:199], v[106:109]
	v_mfma_f32_16x16x32_bf16 v[98:101], v[158:161], v[196:199], v[98:101]
	v_mfma_f32_16x16x32_bf16 v[90:93], v[150:153], v[204:207], v[90:93]
	v_mfma_f32_16x16x32_bf16 v[82:85], v[158:161], v[204:207], v[82:85]
	v_mfma_f32_16x16x32_bf16 v[74:77], v[150:153], v[212:215], v[74:77]
	v_mfma_f32_16x16x32_bf16 v[66:69], v[158:161], v[212:215], v[66:69]
	s_setprio 0
	s_barrier
	s_add_i32 s34, s53, s42
	v_lshl_add_u64 v[216:217], v[216:217], 0, s[54:55]
	s_mov_b32 m0, s34
	ds_read_b128 v[184:187], v238 offset:49152
	ds_read_b128 v[188:191], v238 offset:50176
	ds_read_b128 v[192:195], v238 offset:51200
	ds_read_b128 v[196:199], v238 offset:52224
	ds_read_b128 v[200:203], v238 offset:53248
	ds_read_b128 v[204:207], v238 offset:54272
	ds_read_b128 v[208:211], v238 offset:55296
	ds_read_b128 v[212:215], v238 offset:56320
	global_load_lds_dwordx4 v[216:217], off
	s_add_i32 m0, s34, 0x2000
	s_add_u32 s30, s30, 0x40080
	v_lshl_add_u64 v[216:217], v[218:219], 0, s[54:55]
	s_addc_u32 s31, s31, 0
	s_add_i32 s34, s60, s42
	global_load_lds_dwordx4 v[216:217], off
	v_lshl_add_u64 v[216:217], s[30:31], 0, v[0:1]
	s_mov_b32 m0, s34
	s_nop 0
	global_load_lds_dwordx4 v[216:217], off
	v_lshl_add_u64 v[216:217], s[30:31], 0, v[166:167]
	s_add_i32 m0, s34, 0x2000
	s_nop 0
	global_load_lds_dwordx4 v[216:217], off
	v_lshl_add_u64 v[216:217], v[222:223], 0, s[54:55]
	s_mov_b32 m0, s56
	s_nop 0
	global_load_lds_dwordx4 v[216:217], off
	v_lshl_add_u64 v[216:217], v[232:233], 0, s[54:55]
	s_mov_b32 m0, s57
	s_nop 0
	global_load_lds_dwordx4 v[216:217], off
	s_waitcnt vmcnt(8)
	s_waitcnt lgkmcnt(0)
	s_barrier
	s_setprio 1
	v_mfma_f32_16x16x32_bf16 v[62:65], v[114:117], v[184:187], v[62:65]
	v_mfma_f32_16x16x32_bf16 v[54:57], v[130:133], v[184:187], v[54:57]
	v_mfma_f32_16x16x32_bf16 v[46:49], v[114:117], v[192:195], v[46:49]
	v_mfma_f32_16x16x32_bf16 v[38:41], v[130:133], v[192:195], v[38:41]
	v_mfma_f32_16x16x32_bf16 v[30:33], v[114:117], v[200:203], v[30:33]
	v_mfma_f32_16x16x32_bf16 v[22:25], v[130:133], v[200:203], v[22:25]
	v_mfma_f32_16x16x32_bf16 v[14:17], v[114:117], v[208:211], v[14:17]
	v_mfma_f32_16x16x32_bf16 v[6:9], v[130:133], v[208:211], v[6:9]
	v_mfma_f32_16x16x32_bf16 v[62:65], v[122:125], v[188:191], v[62:65]
	v_mfma_f32_16x16x32_bf16 v[54:57], v[142:145], v[188:191], v[54:57]
	v_mfma_f32_16x16x32_bf16 v[46:49], v[122:125], v[196:199], v[46:49]
	v_mfma_f32_16x16x32_bf16 v[38:41], v[142:145], v[196:199], v[38:41]
	v_mfma_f32_16x16x32_bf16 v[30:33], v[122:125], v[204:207], v[30:33]
	v_mfma_f32_16x16x32_bf16 v[22:25], v[142:145], v[204:207], v[22:25]
	v_mfma_f32_16x16x32_bf16 v[14:17], v[122:125], v[212:215], v[14:17]
	v_mfma_f32_16x16x32_bf16 v[6:9], v[142:145], v[212:215], v[6:9]
	v_mfma_f32_16x16x32_bf16 v[58:61], v[146:149], v[184:187], v[58:61]
	v_mfma_f32_16x16x32_bf16 v[50:53], v[154:157], v[184:187], v[50:53]
	v_mfma_f32_16x16x32_bf16 v[42:45], v[146:149], v[192:195], v[42:45]
	v_mfma_f32_16x16x32_bf16 v[34:37], v[154:157], v[192:195], v[34:37]
	v_mfma_f32_16x16x32_bf16 v[26:29], v[146:149], v[200:203], v[26:29]
	v_mfma_f32_16x16x32_bf16 v[18:21], v[154:157], v[200:203], v[18:21]
	v_mfma_f32_16x16x32_bf16 v[10:13], v[146:149], v[208:211], v[10:13]
	v_mfma_f32_16x16x32_bf16 v[2:5], v[154:157], v[208:211], v[2:5]
	v_mfma_f32_16x16x32_bf16 v[58:61], v[150:153], v[188:191], v[58:61]
	v_mfma_f32_16x16x32_bf16 v[50:53], v[158:161], v[188:191], v[50:53]
	v_mfma_f32_16x16x32_bf16 v[42:45], v[150:153], v[196:199], v[42:45]
	v_mfma_f32_16x16x32_bf16 v[34:37], v[158:161], v[196:199], v[34:37]
	v_mfma_f32_16x16x32_bf16 v[26:29], v[150:153], v[204:207], v[26:29]
	v_mfma_f32_16x16x32_bf16 v[18:21], v[158:161], v[204:207], v[18:21]
	v_mfma_f32_16x16x32_bf16 v[10:13], v[150:153], v[212:215], v[10:13]
	v_mfma_f32_16x16x32_bf16 v[2:5], v[158:161], v[212:215], v[2:5]
	s_setprio 0
	s_barrier
	s_add_i32 s50, s50, 2
	s_add_u32 s28, s28, 0x100
	s_addc_u32 s29, s29, 0
	s_add_u32 s25, s25, 0x100
	s_addc_u32 s27, s27, 0
	s_cmp_gt_u32 s50, 13
	s_cbranch_scc0 .LBB0_501
	s_and_b64 vcc, exec, s[14:15]
	s_cbranch_vccz .LBB0_504
	s_barrier

.LBB0_613:
	s_add_u32 s38, s8, 0xfffc0080
	s_addc_u32 s39, s9, -1
	s_add_i32 s53, 0, 0x10000
	s_cmp_eq_u32 s43, 12
	s_cselect_b32 s41, s2, s39
	s_cselect_b32 s40, s3, s38
	v_add_u32_e32 v0, s53, v182
	s_cselect_b32 s39, s11, s42
	s_cselect_b32 s38, s27, s29
	s_add_i32 s60, 0, 0x14000
	ds_read_b128 v[106:109], v0
	ds_read_b128 v[110:113], v0 offset:1024
	ds_read_b128 v[114:117], v0 offset:2048
	ds_read_b128 v[118:121], v0 offset:3072
	v_add_u32_e32 v0, s60, v182
	ds_read_b128 v[160:163], v0
	ds_read_b128 v[164:167], v0 offset:1024
	ds_read_b128 v[194:197], v0 offset:2048
	ds_read_b128 v[198:201], v0 offset:3072
	v_lshl_add_u64 v[168:169], s[8:9], 0, v[154:155]
	s_add_i32 m0, s37, 0xc000
	ds_read_b128 v[202:205], v192
	ds_read_b128 v[206:209], v192 offset:1024
	ds_read_b128 v[210:213], v192 offset:2048
	ds_read_b128 v[214:217], v192 offset:3072
	ds_read_b128 v[236:239], v192 offset:4096
	ds_read_b128 v[240:243], v192 offset:5120
	ds_read_b128 v[244:247], v192 offset:6144
	ds_read_b128 v[248:251], v192 offset:7168
	global_load_lds_dwordx4 v[168:169], off
	v_lshl_add_u64 v[168:169], s[8:9], 0, v[156:157]
	s_add_i32 m0, s37, 0xe000
	s_nop 0
	global_load_lds_dwordx4 v[168:169], off
	s_waitcnt vmcnt(8)
	s_waitcnt lgkmcnt(0)
	s_barrier
	s_setprio 1
	v_mfma_f32_16x16x32_bf16 v[70:73], v[106:109], v[202:205], v[70:73]
	v_mfma_f32_16x16x32_bf16 v[66:69], v[114:117], v[202:205], v[66:69]
	v_mfma_f32_16x16x32_bf16 v[54:57], v[106:109], v[210:213], v[54:57]
	v_mfma_f32_16x16x32_bf16 v[50:53], v[114:117], v[210:213], v[50:53]
	v_mfma_f32_16x16x32_bf16 v[46:49], v[106:109], v[236:239], v[46:49]
	v_mfma_f32_16x16x32_bf16 v[42:45], v[114:117], v[236:239], v[42:45]
	v_mfma_f32_16x16x32_bf16 v[38:41], v[106:109], v[244:247], v[38:41]
	v_mfma_f32_16x16x32_bf16 v[34:37], v[114:117], v[244:247], v[34:37]
	v_mfma_f32_16x16x32_bf16 v[70:73], v[110:113], v[206:209], v[70:73]
	v_mfma_f32_16x16x32_bf16 v[66:69], v[118:121], v[206:209], v[66:69]
	v_mfma_f32_16x16x32_bf16 v[54:57], v[110:113], v[214:217], v[54:57]
	v_mfma_f32_16x16x32_bf16 v[50:53], v[118:121], v[214:217], v[50:53]
	v_mfma_f32_16x16x32_bf16 v[46:49], v[110:113], v[240:243], v[46:49]
	v_mfma_f32_16x16x32_bf16 v[42:45], v[118:121], v[240:243], v[42:45]
	v_mfma_f32_16x16x32_bf16 v[38:41], v[110:113], v[248:251], v[38:41]
	v_mfma_f32_16x16x32_bf16 v[34:37], v[118:121], v[248:251], v[34:37]
	v_mfma_f32_16x16x32_bf16 v[142:145], v[160:163], v[202:205], v[142:145]
	v_mfma_f32_16x16x32_bf16 v[138:141], v[194:197], v[202:205], v[138:141]
	v_mfma_f32_16x16x32_bf16 v[134:137], v[160:163], v[210:213], v[134:137]
	v_mfma_f32_16x16x32_bf16 v[130:133], v[194:197], v[210:213], v[130:133]
	v_mfma_f32_16x16x32_bf16 v[126:129], v[160:163], v[236:239], v[126:129]
	v_mfma_f32_16x16x32_bf16 v[122:125], v[194:197], v[236:239], v[122:125]
	v_mfma_f32_16x16x32_bf16 v[102:105], v[160:163], v[244:247], v[102:105]
	v_mfma_f32_16x16x32_bf16 v[98:101], v[194:197], v[244:247], v[98:101]
	v_mfma_f32_16x16x32_bf16 v[142:145], v[164:167], v[206:209], v[142:145]
	v_mfma_f32_16x16x32_bf16 v[138:141], v[198:201], v[206:209], v[138:141]
	v_mfma_f32_16x16x32_bf16 v[134:137], v[164:167], v[214:217], v[134:137]
	v_mfma_f32_16x16x32_bf16 v[130:133], v[198:201], v[214:217], v[130:133]
	v_mfma_f32_16x16x32_bf16 v[126:129], v[164:167], v[240:243], v[126:129]
	v_mfma_f32_16x16x32_bf16 v[122:125], v[198:201], v[240:243], v[122:125]
	v_mfma_f32_16x16x32_bf16 v[102:105], v[164:167], v[248:251], v[102:105]
	v_mfma_f32_16x16x32_bf16 v[98:101], v[198:201], v[248:251], v[98:101]
	s_setprio 0
	s_barrier
	s_add_i32 s53, s53, s57
	v_lshl_add_u64 v[168:169], s[38:39], 0, v[148:149]
	s_mov_b32 m0, s53
	ds_read_b128 v[202:205], v192 offset:16384
	ds_read_b128 v[206:209], v192 offset:17408
	ds_read_b128 v[210:213], v192 offset:18432
	ds_read_b128 v[214:217], v192 offset:19456
	ds_read_b128 v[236:239], v192 offset:20480
	ds_read_b128 v[240:243], v192 offset:21504
	ds_read_b128 v[244:247], v192 offset:22528
	ds_read_b128 v[248:251], v192 offset:23552
	global_load_lds_dwordx4 v[168:169], off
	s_add_i32 m0, s53, 0x2000
	s_add_u32 s64, s38, 0x40000
	v_lshl_add_u64 v[218:219], s[38:39], 0, v[152:153]
	s_addc_u32 s65, s39, 0
	s_add_i32 s53, s60, s57
	global_load_lds_dwordx4 v[218:219], off
	v_lshl_add_u64 v[252:253], s[64:65], 0, v[148:149]
	s_mov_b32 m0, s53
	v_lshl_add_u64 v[232:233], s[40:41], 0, v[150:151]
	global_load_lds_dwordx4 v[252:253], off
	v_lshl_add_u64 v[252:253], s[64:65], 0, v[152:153]
	s_add_i32 m0, s53, 0x2000
	s_nop 0
	global_load_lds_dwordx4 v[252:253], off
	v_lshl_add_u64 v[252:253], s[40:41], 0, v[146:147]
	s_mov_b32 m0, s37
	s_nop 0
	global_load_lds_dwordx4 v[252:253], off
	s_mov_b32 m0, s58
	s_nop 0
	global_load_lds_dwordx4 v[232:233], off
	s_waitcnt vmcnt(8)
	s_waitcnt lgkmcnt(0)
	s_barrier
	s_setprio 1
	v_mfma_f32_16x16x32_bf16 v[30:33], v[106:109], v[202:205], v[30:33]
	v_mfma_f32_16x16x32_bf16 v[26:29], v[114:117], v[202:205], v[26:29]
	v_mfma_f32_16x16x32_bf16 v[22:25], v[106:109], v[210:213], v[22:25]
	v_mfma_f32_16x16x32_bf16 v[18:21], v[114:117], v[210:213], v[18:21]
	v_mfma_f32_16x16x32_bf16 v[14:17], v[106:109], v[236:239], v[14:17]
	v_mfma_f32_16x16x32_bf16 v[10:13], v[114:117], v[236:239], v[10:13]
	v_mfma_f32_16x16x32_bf16 v[6:9], v[106:109], v[244:247], v[6:9]
	v_mfma_f32_16x16x32_bf16 v[2:5], v[114:117], v[244:247], v[2:5]
	v_mfma_f32_16x16x32_bf16 v[30:33], v[110:113], v[206:209], v[30:33]
	v_mfma_f32_16x16x32_bf16 v[26:29], v[118:121], v[206:209], v[26:29]
	v_mfma_f32_16x16x32_bf16 v[22:25], v[110:113], v[214:217], v[22:25]
	v_mfma_f32_16x16x32_bf16 v[18:21], v[118:121], v[214:217], v[18:21]
	v_mfma_f32_16x16x32_bf16 v[14:17], v[110:113], v[240:243], v[14:17]
	v_mfma_f32_16x16x32_bf16 v[10:13], v[118:121], v[240:243], v[10:13]
	v_mfma_f32_16x16x32_bf16 v[6:9], v[110:113], v[248:251], v[6:9]
	v_mfma_f32_16x16x32_bf16 v[2:5], v[118:121], v[248:251], v[2:5]
	v_mfma_f32_16x16x32_bf16 v[94:97], v[160:163], v[202:205], v[94:97]
	v_mfma_f32_16x16x32_bf16 v[90:93], v[194:197], v[202:205], v[90:93]
	v_mfma_f32_16x16x32_bf16 v[86:89], v[160:163], v[210:213], v[86:89]
	v_mfma_f32_16x16x32_bf16 v[82:85], v[194:197], v[210:213], v[82:85]
	v_mfma_f32_16x16x32_bf16 v[78:81], v[160:163], v[236:239], v[78:81]
	v_mfma_f32_16x16x32_bf16 v[74:77], v[194:197], v[236:239], v[74:77]
	v_mfma_f32_16x16x32_bf16 v[62:65], v[160:163], v[244:247], v[62:65]
	v_mfma_f32_16x16x32_bf16 v[58:61], v[194:197], v[244:247], v[58:61]
	v_mfma_f32_16x16x32_bf16 v[94:97], v[164:167], v[206:209], v[94:97]
	v_mfma_f32_16x16x32_bf16 v[90:93], v[198:201], v[206:209], v[90:93]
	v_mfma_f32_16x16x32_bf16 v[86:89], v[164:167], v[214:217], v[86:89]
	v_mfma_f32_16x16x32_bf16 v[82:85], v[198:201], v[214:217], v[82:85]
	v_mfma_f32_16x16x32_bf16 v[78:81], v[164:167], v[240:243], v[78:81]
	v_mfma_f32_16x16x32_bf16 v[74:77], v[198:201], v[240:243], v[74:77]
	v_mfma_f32_16x16x32_bf16 v[62:65], v[164:167], v[248:251], v[62:65]
	v_mfma_f32_16x16x32_bf16 v[58:61], v[198:201], v[248:251], v[58:61]
	s_setprio 0
	s_barrier
	s_add_i32 s53, 0, 0x18000
	v_add_u32_e32 v0, s53, v182
	s_add_i32 s60, 0, 0x1c000
	ds_read_b128 v[106:109], v0
	ds_read_b128 v[110:113], v0 offset:1024
	ds_read_b128 v[114:117], v0 offset:2048
	ds_read_b128 v[118:121], v0 offset:3072
	v_add_u32_e32 v0, s60, v182
	ds_read_b128 v[160:163], v0
	ds_read_b128 v[164:167], v0 offset:1024
	ds_read_b128 v[194:197], v0 offset:2048
	ds_read_b128 v[198:201], v0 offset:3072
	s_add_u32 s40, s40, 0x40000
	s_addc_u32 s41, s41, 0
	s_mov_b32 m0, s59
	v_lshl_add_u64 v[222:223], s[40:41], 0, v[146:147]
	ds_read_b128 v[202:205], v192 offset:32768
	ds_read_b128 v[206:209], v192 offset:33792
	ds_read_b128 v[210:213], v192 offset:34816
	ds_read_b128 v[214:217], v192 offset:35840
	ds_read_b128 v[236:239], v192 offset:36864
	ds_read_b128 v[240:243], v192 offset:37888
	ds_read_b128 v[244:247], v192 offset:38912
	ds_read_b128 v[248:251], v192 offset:39936
	global_load_lds_dwordx4 v[222:223], off
	v_lshl_add_u64 v[222:223], s[40:41], 0, v[150:151]
	s_mov_b32 m0, s74
	s_nop 0
	global_load_lds_dwordx4 v[222:223], off
	s_waitcnt vmcnt(8)
	s_waitcnt lgkmcnt(0)
	s_barrier
	s_setprio 1
	v_mfma_f32_16x16x32_bf16 v[70:73], v[106:109], v[202:205], v[70:73]
	v_mfma_f32_16x16x32_bf16 v[66:69], v[114:117], v[202:205], v[66:69]
	v_mfma_f32_16x16x32_bf16 v[54:57], v[106:109], v[210:213], v[54:57]
	v_mfma_f32_16x16x32_bf16 v[50:53], v[114:117], v[210:213], v[50:53]
	v_mfma_f32_16x16x32_bf16 v[46:49], v[106:109], v[236:239], v[46:49]
	v_mfma_f32_16x16x32_bf16 v[42:45], v[114:117], v[236:239], v[42:45]
	v_mfma_f32_16x16x32_bf16 v[38:41], v[106:109], v[244:247], v[38:41]
	v_mfma_f32_16x16x32_bf16 v[34:37], v[114:117], v[244:247], v[34:37]
	v_mfma_f32_16x16x32_bf16 v[70:73], v[110:113], v[206:209], v[70:73]
	v_mfma_f32_16x16x32_bf16 v[66:69], v[118:121], v[206:209], v[66:69]
	v_mfma_f32_16x16x32_bf16 v[54:57], v[110:113], v[214:217], v[54:57]
	v_mfma_f32_16x16x32_bf16 v[50:53], v[118:121], v[214:217], v[50:53]
	v_mfma_f32_16x16x32_bf16 v[46:49], v[110:113], v[240:243], v[46:49]
	v_mfma_f32_16x16x32_bf16 v[42:45], v[118:121], v[240:243], v[42:45]
	v_mfma_f32_16x16x32_bf16 v[38:41], v[110:113], v[248:251], v[38:41]
	v_mfma_f32_16x16x32_bf16 v[34:37], v[118:121], v[248:251], v[34:37]
	v_mfma_f32_16x16x32_bf16 v[142:145], v[160:163], v[202:205], v[142:145]
	v_mfma_f32_16x16x32_bf16 v[138:141], v[194:197], v[202:205], v[138:141]
	v_mfma_f32_16x16x32_bf16 v[134:137], v[160:163], v[210:213], v[134:137]
	v_mfma_f32_16x16x32_bf16 v[130:133], v[194:197], v[210:213], v[130:133]
	v_mfma_f32_16x16x32_bf16 v[126:129], v[160:163], v[236:239], v[126:129]
	v_mfma_f32_16x16x32_bf16 v[122:125], v[194:197], v[236:239], v[122:125]
	v_mfma_f32_16x16x32_bf16 v[102:105], v[160:163], v[244:247], v[102:105]
	v_mfma_f32_16x16x32_bf16 v[98:101], v[194:197], v[244:247], v[98:101]
	v_mfma_f32_16x16x32_bf16 v[142:145], v[164:167], v[206:209], v[142:145]
	v_mfma_f32_16x16x32_bf16 v[138:141], v[198:201], v[206:209], v[138:141]
	v_mfma_f32_16x16x32_bf16 v[134:137], v[164:167], v[214:217], v[134:137]
	v_mfma_f32_16x16x32_bf16 v[130:133], v[198:201], v[214:217], v[130:133]
	v_mfma_f32_16x16x32_bf16 v[126:129], v[164:167], v[240:243], v[126:129]
	v_mfma_f32_16x16x32_bf16 v[122:125], v[198:201], v[240:243], v[122:125]
	v_mfma_f32_16x16x32_bf16 v[102:105], v[164:167], v[248:251], v[102:105]
	v_mfma_f32_16x16x32_bf16 v[98:101], v[198:201], v[248:251], v[98:101]
	s_setprio 0
	s_barrier
	s_add_i32 s40, s53, s57
	v_lshl_add_u64 v[168:169], v[168:169], 0, s[54:55]
	s_mov_b32 m0, s40
	ds_read_b128 v[202:205], v192 offset:49152
	ds_read_b128 v[206:209], v192 offset:50176
	ds_read_b128 v[210:213], v192 offset:51200
	ds_read_b128 v[214:217], v192 offset:52224
	ds_read_b128 v[236:239], v192 offset:53248
	ds_read_b128 v[240:243], v192 offset:54272
	ds_read_b128 v[244:247], v192 offset:55296
	ds_read_b128 v[248:251], v192 offset:56320
	global_load_lds_dwordx4 v[168:169], off
	s_add_i32 m0, s40, 0x2000
	s_add_u32 s38, s38, 0x40080
	v_lshl_add_u64 v[168:169], v[218:219], 0, s[54:55]
	s_addc_u32 s39, s39, 0
	s_add_i32 s40, s60, s57
	global_load_lds_dwordx4 v[168:169], off
	v_lshl_add_u64 v[168:169], s[38:39], 0, v[148:149]
	s_mov_b32 m0, s40
	s_nop 0
	global_load_lds_dwordx4 v[168:169], off
	v_lshl_add_u64 v[168:169], s[38:39], 0, v[152:153]
	s_add_i32 m0, s40, 0x2000
	s_nop 0
	global_load_lds_dwordx4 v[168:169], off
	v_lshl_add_u64 v[168:169], v[252:253], 0, s[54:55]
	s_mov_b32 m0, s79
	s_nop 0
	global_load_lds_dwordx4 v[168:169], off
	v_lshl_add_u64 v[168:169], v[232:233], 0, s[54:55]
	s_mov_b32 m0, s80
	s_nop 0
	global_load_lds_dwordx4 v[168:169], off
	s_waitcnt vmcnt(8)
	s_waitcnt lgkmcnt(0)
	s_barrier
	s_setprio 1
	v_mfma_f32_16x16x32_bf16 v[30:33], v[106:109], v[202:205], v[30:33]
	v_mfma_f32_16x16x32_bf16 v[26:29], v[114:117], v[202:205], v[26:29]
	v_mfma_f32_16x16x32_bf16 v[22:25], v[106:109], v[210:213], v[22:25]
	v_mfma_f32_16x16x32_bf16 v[18:21], v[114:117], v[210:213], v[18:21]
	v_mfma_f32_16x16x32_bf16 v[14:17], v[106:109], v[236:239], v[14:17]
	v_mfma_f32_16x16x32_bf16 v[10:13], v[114:117], v[236:239], v[10:13]
	v_mfma_f32_16x16x32_bf16 v[6:9], v[106:109], v[244:247], v[6:9]
	v_mfma_f32_16x16x32_bf16 v[2:5], v[114:117], v[244:247], v[2:5]
	v_mfma_f32_16x16x32_bf16 v[30:33], v[110:113], v[206:209], v[30:33]
	v_mfma_f32_16x16x32_bf16 v[26:29], v[118:121], v[206:209], v[26:29]
	v_mfma_f32_16x16x32_bf16 v[22:25], v[110:113], v[214:217], v[22:25]
	v_mfma_f32_16x16x32_bf16 v[18:21], v[118:121], v[214:217], v[18:21]
	v_mfma_f32_16x16x32_bf16 v[14:17], v[110:113], v[240:243], v[14:17]
	v_mfma_f32_16x16x32_bf16 v[10:13], v[118:121], v[240:243], v[10:13]
	v_mfma_f32_16x16x32_bf16 v[6:9], v[110:113], v[248:251], v[6:9]
	v_mfma_f32_16x16x32_bf16 v[2:5], v[118:121], v[248:251], v[2:5]
	v_mfma_f32_16x16x32_bf16 v[94:97], v[160:163], v[202:205], v[94:97]
	v_mfma_f32_16x16x32_bf16 v[90:93], v[194:197], v[202:205], v[90:93]
	v_mfma_f32_16x16x32_bf16 v[86:89], v[160:163], v[210:213], v[86:89]
	v_mfma_f32_16x16x32_bf16 v[82:85], v[194:197], v[210:213], v[82:85]
	v_mfma_f32_16x16x32_bf16 v[78:81], v[160:163], v[236:239], v[78:81]
	v_mfma_f32_16x16x32_bf16 v[74:77], v[194:197], v[236:239], v[74:77]
	v_mfma_f32_16x16x32_bf16 v[62:65], v[160:163], v[244:247], v[62:65]
	v_mfma_f32_16x16x32_bf16 v[58:61], v[194:197], v[244:247], v[58:61]
	v_mfma_f32_16x16x32_bf16 v[94:97], v[164:167], v[206:209], v[94:97]
	v_mfma_f32_16x16x32_bf16 v[90:93], v[198:201], v[206:209], v[90:93]
	v_mfma_f32_16x16x32_bf16 v[86:89], v[164:167], v[214:217], v[86:89]
	v_mfma_f32_16x16x32_bf16 v[82:85], v[198:201], v[214:217], v[82:85]
	v_mfma_f32_16x16x32_bf16 v[78:81], v[164:167], v[240:243], v[78:81]
	v_mfma_f32_16x16x32_bf16 v[74:77], v[198:201], v[240:243], v[74:77]
	v_mfma_f32_16x16x32_bf16 v[62:65], v[164:167], v[248:251], v[62:65]
	v_mfma_f32_16x16x32_bf16 v[58:61], v[198:201], v[248:251], v[58:61]
	s_setprio 0
	s_barrier
	s_add_i32 s43, s43, 2
	s_add_u32 s8, s8, 0x100
	s_addc_u32 s9, s9, 0
	s_add_u32 s29, s29, 0x100
	s_addc_u32 s42, s42, 0
	s_cmp_gt_u32 s43, 13
	s_cbranch_scc0 .LBB0_613
	s_and_b64 vcc, exec, s[24:25]
	s_cbranch_vccz .LBB0_620
	s_barrier
	s_cmp_lg_u32 s10, 12
	s_mov_b64 s[8:9], -1
	s_cbranch_scc1 .LBB0_621

.LBB0_973:
	s_add_u32 s30, s28, 0xfffc0080
	s_addc_u32 s31, s29, -1
	s_add_i32 s53, 0, 0x10000
	s_cmp_eq_u32 s50, 12
	s_cselect_b32 s35, s2, s31
	s_cselect_b32 s34, s3, s30
	s_cselect_b32 s31, s17, s27
	s_cselect_b32 s30, s19, s25
	s_add_i32 s60, 0, 0x14000
	v_add_u32_e32 v142, s53, v200
	v_add_u32_e32 v180, s60, v200
	ds_read_b128 v[130:133], v142
	ds_read_b128 v[134:137], v142 offset:1024
	ds_read_b128 v[138:141], v142 offset:2048
	ds_read_b128 v[142:145], v142 offset:3072
	ds_read_b128 v[146:149], v180
	ds_read_b128 v[150:153], v180 offset:1024
	ds_read_b128 v[154:157], v180 offset:2048
	ds_read_b128 v[180:183], v180 offset:3072
	v_lshl_add_u64 v[222:223], s[28:29], 0, v[166:167]
	s_add_i32 m0, s43, 0xc000
	ds_read_b128 v[184:187], v202
	ds_read_b128 v[188:191], v202 offset:1024
	ds_read_b128 v[192:195], v202 offset:2048
	ds_read_b128 v[196:199], v202 offset:3072
	ds_read_b128 v[204:207], v202 offset:4096
	ds_read_b128 v[208:211], v202 offset:5120
	ds_read_b128 v[212:215], v202 offset:6144
	ds_read_b128 v[216:219], v202 offset:7168
	global_load_lds_dwordx4 v[222:223], off
	v_lshl_add_u64 v[222:223], s[28:29], 0, v[168:169]
	s_add_i32 m0, s43, 0xe000
	s_nop 0
	global_load_lds_dwordx4 v[222:223], off
	s_waitcnt vmcnt(8)
	s_waitcnt lgkmcnt(0)
	s_barrier
	s_setprio 1
	v_mfma_f32_16x16x32_bf16 v[126:129], v[130:133], v[184:187], v[126:129]
	v_mfma_f32_16x16x32_bf16 v[122:125], v[138:141], v[184:187], v[122:125]
	v_mfma_f32_16x16x32_bf16 v[110:113], v[130:133], v[192:195], v[110:113]
	v_mfma_f32_16x16x32_bf16 v[106:109], v[138:141], v[192:195], v[106:109]
	v_mfma_f32_16x16x32_bf16 v[94:97], v[130:133], v[204:207], v[94:97]
	v_mfma_f32_16x16x32_bf16 v[90:93], v[138:141], v[204:207], v[90:93]
	v_mfma_f32_16x16x32_bf16 v[78:81], v[130:133], v[212:215], v[78:81]
	v_mfma_f32_16x16x32_bf16 v[74:77], v[138:141], v[212:215], v[74:77]
	v_mfma_f32_16x16x32_bf16 v[126:129], v[134:137], v[188:191], v[126:129]
	v_mfma_f32_16x16x32_bf16 v[122:125], v[142:145], v[188:191], v[122:125]
	v_mfma_f32_16x16x32_bf16 v[110:113], v[134:137], v[196:199], v[110:113]
	v_mfma_f32_16x16x32_bf16 v[106:109], v[142:145], v[196:199], v[106:109]
	v_mfma_f32_16x16x32_bf16 v[94:97], v[134:137], v[208:211], v[94:97]
	v_mfma_f32_16x16x32_bf16 v[90:93], v[142:145], v[208:211], v[90:93]
	v_mfma_f32_16x16x32_bf16 v[78:81], v[134:137], v[216:219], v[78:81]
	v_mfma_f32_16x16x32_bf16 v[74:77], v[142:145], v[216:219], v[74:77]
	v_mfma_f32_16x16x32_bf16 v[118:121], v[146:149], v[184:187], v[118:121]
	v_mfma_f32_16x16x32_bf16 v[114:117], v[154:157], v[184:187], v[114:117]
	v_mfma_f32_16x16x32_bf16 v[102:105], v[146:149], v[192:195], v[102:105]
	v_mfma_f32_16x16x32_bf16 v[98:101], v[154:157], v[192:195], v[98:101]
	v_mfma_f32_16x16x32_bf16 v[86:89], v[146:149], v[204:207], v[86:89]
	v_mfma_f32_16x16x32_bf16 v[82:85], v[154:157], v[204:207], v[82:85]
	v_mfma_f32_16x16x32_bf16 v[70:73], v[146:149], v[212:215], v[70:73]
	v_mfma_f32_16x16x32_bf16 v[66:69], v[154:157], v[212:215], v[66:69]
	v_mfma_f32_16x16x32_bf16 v[118:121], v[150:153], v[188:191], v[118:121]
	v_mfma_f32_16x16x32_bf16 v[114:117], v[180:183], v[188:191], v[114:117]
	v_mfma_f32_16x16x32_bf16 v[102:105], v[150:153], v[196:199], v[102:105]
	v_mfma_f32_16x16x32_bf16 v[98:101], v[180:183], v[196:199], v[98:101]
	v_mfma_f32_16x16x32_bf16 v[86:89], v[150:153], v[208:211], v[86:89]
	v_mfma_f32_16x16x32_bf16 v[82:85], v[180:183], v[208:211], v[82:85]
	v_mfma_f32_16x16x32_bf16 v[70:73], v[150:153], v[216:219], v[70:73]
	v_mfma_f32_16x16x32_bf16 v[66:69], v[180:183], v[216:219], v[66:69]
	s_setprio 0
	s_barrier
	s_add_i32 s53, s53, s42
	v_lshl_add_u64 v[222:223], s[30:31], 0, v[0:1]
	s_mov_b32 m0, s53
	ds_read_b128 v[184:187], v202 offset:16384
	ds_read_b128 v[188:191], v202 offset:17408
	ds_read_b128 v[192:195], v202 offset:18432
	ds_read_b128 v[196:199], v202 offset:19456
	ds_read_b128 v[204:207], v202 offset:20480
	ds_read_b128 v[208:211], v202 offset:21504
	ds_read_b128 v[212:215], v202 offset:22528
	ds_read_b128 v[216:219], v202 offset:23552
	global_load_lds_dwordx4 v[222:223], off
	s_add_i32 m0, s53, 0x2000
	s_add_u32 s64, s30, 0x40000
	v_lshl_add_u64 v[232:233], s[30:31], 0, v[162:163]
	s_addc_u32 s65, s31, 0
	s_add_i32 s53, s60, s42
	global_load_lds_dwordx4 v[232:233], off
	v_lshl_add_u64 v[236:237], s[64:65], 0, v[0:1]
	s_mov_b32 m0, s53
	v_lshl_add_u64 v[238:239], s[34:35], 0, v[160:161]
	global_load_lds_dwordx4 v[236:237], off
	v_lshl_add_u64 v[236:237], s[64:65], 0, v[162:163]
	s_add_i32 m0, s53, 0x2000
	s_nop 0
	global_load_lds_dwordx4 v[236:237], off
	v_lshl_add_u64 v[236:237], s[34:35], 0, v[158:159]
	s_mov_b32 m0, s43
	s_nop 0
	global_load_lds_dwordx4 v[236:237], off
	s_mov_b32 m0, s45
	s_nop 0
	global_load_lds_dwordx4 v[238:239], off
	s_waitcnt vmcnt(8)
	s_waitcnt lgkmcnt(0)
	s_barrier
	s_setprio 1
	v_mfma_f32_16x16x32_bf16 v[62:65], v[130:133], v[184:187], v[62:65]
	v_mfma_f32_16x16x32_bf16 v[58:61], v[138:141], v[184:187], v[58:61]
	v_mfma_f32_16x16x32_bf16 v[46:49], v[130:133], v[192:195], v[46:49]
	v_mfma_f32_16x16x32_bf16 v[42:45], v[138:141], v[192:195], v[42:45]
	v_mfma_f32_16x16x32_bf16 v[30:33], v[130:133], v[204:207], v[30:33]
	v_mfma_f32_16x16x32_bf16 v[26:29], v[138:141], v[204:207], v[26:29]
	v_mfma_f32_16x16x32_bf16 v[14:17], v[130:133], v[212:215], v[14:17]
	v_mfma_f32_16x16x32_bf16 v[10:13], v[138:141], v[212:215], v[10:13]
	v_mfma_f32_16x16x32_bf16 v[62:65], v[134:137], v[188:191], v[62:65]
	v_mfma_f32_16x16x32_bf16 v[58:61], v[142:145], v[188:191], v[58:61]
	v_mfma_f32_16x16x32_bf16 v[46:49], v[134:137], v[196:199], v[46:49]
	v_mfma_f32_16x16x32_bf16 v[42:45], v[142:145], v[196:199], v[42:45]
	v_mfma_f32_16x16x32_bf16 v[30:33], v[134:137], v[208:211], v[30:33]
	v_mfma_f32_16x16x32_bf16 v[26:29], v[142:145], v[208:211], v[26:29]
	v_mfma_f32_16x16x32_bf16 v[14:17], v[134:137], v[216:219], v[14:17]
	v_mfma_f32_16x16x32_bf16 v[10:13], v[142:145], v[216:219], v[10:13]
	v_mfma_f32_16x16x32_bf16 v[54:57], v[146:149], v[184:187], v[54:57]
	v_mfma_f32_16x16x32_bf16 v[50:53], v[154:157], v[184:187], v[50:53]
	v_mfma_f32_16x16x32_bf16 v[38:41], v[146:149], v[192:195], v[38:41]
	v_mfma_f32_16x16x32_bf16 v[34:37], v[154:157], v[192:195], v[34:37]
	v_mfma_f32_16x16x32_bf16 v[22:25], v[146:149], v[204:207], v[22:25]
	v_mfma_f32_16x16x32_bf16 v[18:21], v[154:157], v[204:207], v[18:21]
	v_mfma_f32_16x16x32_bf16 v[6:9], v[146:149], v[212:215], v[6:9]
	v_mfma_f32_16x16x32_bf16 v[2:5], v[154:157], v[212:215], v[2:5]
	v_mfma_f32_16x16x32_bf16 v[54:57], v[150:153], v[188:191], v[54:57]
	v_mfma_f32_16x16x32_bf16 v[50:53], v[180:183], v[188:191], v[50:53]
	v_mfma_f32_16x16x32_bf16 v[38:41], v[150:153], v[196:199], v[38:41]
	v_mfma_f32_16x16x32_bf16 v[34:37], v[180:183], v[196:199], v[34:37]
	v_mfma_f32_16x16x32_bf16 v[22:25], v[150:153], v[208:211], v[22:25]
	v_mfma_f32_16x16x32_bf16 v[18:21], v[180:183], v[208:211], v[18:21]
	v_mfma_f32_16x16x32_bf16 v[6:9], v[150:153], v[216:219], v[6:9]
	v_mfma_f32_16x16x32_bf16 v[2:5], v[180:183], v[216:219], v[2:5]
	s_setprio 0
	s_barrier
	s_add_i32 s53, 0, 0x18000
	s_add_i32 s60, 0, 0x1c000
	v_add_u32_e32 v142, s53, v200
	v_add_u32_e32 v180, s60, v200
	ds_read_b128 v[130:133], v142
	ds_read_b128 v[134:137], v142 offset:1024
	ds_read_b128 v[138:141], v142 offset:2048
	ds_read_b128 v[142:145], v142 offset:3072
	ds_read_b128 v[146:149], v180
	ds_read_b128 v[150:153], v180 offset:1024
	ds_read_b128 v[154:157], v180 offset:2048
	ds_read_b128 v[180:183], v180 offset:3072
	s_add_u32 s34, s34, 0x40000
	s_addc_u32 s35, s35, 0
	s_mov_b32 m0, s46
	v_lshl_add_u64 v[240:241], s[34:35], 0, v[158:159]
	ds_read_b128 v[184:187], v202 offset:32768
	ds_read_b128 v[188:191], v202 offset:33792
	ds_read_b128 v[192:195], v202 offset:34816
	ds_read_b128 v[196:199], v202 offset:35840
	ds_read_b128 v[204:207], v202 offset:36864
	ds_read_b128 v[208:211], v202 offset:37888
	ds_read_b128 v[212:215], v202 offset:38912
	ds_read_b128 v[216:219], v202 offset:39936
	global_load_lds_dwordx4 v[240:241], off
	v_lshl_add_u64 v[240:241], s[34:35], 0, v[160:161]
	s_mov_b32 m0, s47
	s_nop 0
	global_load_lds_dwordx4 v[240:241], off
	s_waitcnt vmcnt(8)
	s_waitcnt lgkmcnt(0)
	s_barrier
	s_setprio 1
	v_mfma_f32_16x16x32_bf16 v[126:129], v[130:133], v[184:187], v[126:129]
	v_mfma_f32_16x16x32_bf16 v[122:125], v[138:141], v[184:187], v[122:125]
	v_mfma_f32_16x16x32_bf16 v[110:113], v[130:133], v[192:195], v[110:113]
	v_mfma_f32_16x16x32_bf16 v[106:109], v[138:141], v[192:195], v[106:109]
	v_mfma_f32_16x16x32_bf16 v[94:97], v[130:133], v[204:207], v[94:97]
	v_mfma_f32_16x16x32_bf16 v[90:93], v[138:141], v[204:207], v[90:93]
	v_mfma_f32_16x16x32_bf16 v[78:81], v[130:133], v[212:215], v[78:81]
	v_mfma_f32_16x16x32_bf16 v[74:77], v[138:141], v[212:215], v[74:77]
	v_mfma_f32_16x16x32_bf16 v[126:129], v[134:137], v[188:191], v[126:129]
	v_mfma_f32_16x16x32_bf16 v[122:125], v[142:145], v[188:191], v[122:125]
	v_mfma_f32_16x16x32_bf16 v[110:113], v[134:137], v[196:199], v[110:113]
	v_mfma_f32_16x16x32_bf16 v[106:109], v[142:145], v[196:199], v[106:109]
	v_mfma_f32_16x16x32_bf16 v[94:97], v[134:137], v[208:211], v[94:97]
	v_mfma_f32_16x16x32_bf16 v[90:93], v[142:145], v[208:211], v[90:93]
	v_mfma_f32_16x16x32_bf16 v[78:81], v[134:137], v[216:219], v[78:81]
	v_mfma_f32_16x16x32_bf16 v[74:77], v[142:145], v[216:219], v[74:77]
	v_mfma_f32_16x16x32_bf16 v[118:121], v[146:149], v[184:187], v[118:121]
	v_mfma_f32_16x16x32_bf16 v[114:117], v[154:157], v[184:187], v[114:117]
	v_mfma_f32_16x16x32_bf16 v[102:105], v[146:149], v[192:195], v[102:105]
	v_mfma_f32_16x16x32_bf16 v[98:101], v[154:157], v[192:195], v[98:101]
	v_mfma_f32_16x16x32_bf16 v[86:89], v[146:149], v[204:207], v[86:89]
	v_mfma_f32_16x16x32_bf16 v[82:85], v[154:157], v[204:207], v[82:85]
	v_mfma_f32_16x16x32_bf16 v[70:73], v[146:149], v[212:215], v[70:73]
	v_mfma_f32_16x16x32_bf16 v[66:69], v[154:157], v[212:215], v[66:69]
	v_mfma_f32_16x16x32_bf16 v[118:121], v[150:153], v[188:191], v[118:121]
	v_mfma_f32_16x16x32_bf16 v[114:117], v[180:183], v[188:191], v[114:117]
	v_mfma_f32_16x16x32_bf16 v[102:105], v[150:153], v[196:199], v[102:105]
	v_mfma_f32_16x16x32_bf16 v[98:101], v[180:183], v[196:199], v[98:101]
	v_mfma_f32_16x16x32_bf16 v[86:89], v[150:153], v[208:211], v[86:89]
	v_mfma_f32_16x16x32_bf16 v[82:85], v[180:183], v[208:211], v[82:85]
	v_mfma_f32_16x16x32_bf16 v[70:73], v[150:153], v[216:219], v[70:73]
	v_mfma_f32_16x16x32_bf16 v[66:69], v[180:183], v[216:219], v[66:69]
	s_setprio 0
	s_barrier
	s_add_i32 s34, s53, s42
	v_lshl_add_u64 v[222:223], v[222:223], 0, s[54:55]
	s_mov_b32 m0, s34
	ds_read_b128 v[184:187], v202 offset:49152
	ds_read_b128 v[188:191], v202 offset:50176
	ds_read_b128 v[192:195], v202 offset:51200
	ds_read_b128 v[196:199], v202 offset:52224
	ds_read_b128 v[204:207], v202 offset:53248
	ds_read_b128 v[208:211], v202 offset:54272
	ds_read_b128 v[212:215], v202 offset:55296
	ds_read_b128 v[216:219], v202 offset:56320
	global_load_lds_dwordx4 v[222:223], off
	s_add_i32 m0, s34, 0x2000
	s_add_u32 s30, s30, 0x40080
	v_lshl_add_u64 v[222:223], v[232:233], 0, s[54:55]
	s_addc_u32 s31, s31, 0
	s_add_i32 s34, s60, s42
	global_load_lds_dwordx4 v[222:223], off
	v_lshl_add_u64 v[222:223], s[30:31], 0, v[0:1]
	s_mov_b32 m0, s34
	s_nop 0
	global_load_lds_dwordx4 v[222:223], off
	v_lshl_add_u64 v[222:223], s[30:31], 0, v[162:163]
	s_add_i32 m0, s34, 0x2000
	s_nop 0
	global_load_lds_dwordx4 v[222:223], off
	v_lshl_add_u64 v[222:223], v[236:237], 0, s[54:55]
	s_mov_b32 m0, s56
	s_nop 0
	global_load_lds_dwordx4 v[222:223], off
	v_lshl_add_u64 v[222:223], v[238:239], 0, s[54:55]
	s_mov_b32 m0, s57
	s_nop 0
	global_load_lds_dwordx4 v[222:223], off
	s_waitcnt vmcnt(8)
	s_waitcnt lgkmcnt(0)
	s_barrier
	s_setprio 1
	v_mfma_f32_16x16x32_bf16 v[62:65], v[130:133], v[184:187], v[62:65]
	v_mfma_f32_16x16x32_bf16 v[58:61], v[138:141], v[184:187], v[58:61]
	v_mfma_f32_16x16x32_bf16 v[46:49], v[130:133], v[192:195], v[46:49]
	v_mfma_f32_16x16x32_bf16 v[42:45], v[138:141], v[192:195], v[42:45]
	v_mfma_f32_16x16x32_bf16 v[30:33], v[130:133], v[204:207], v[30:33]
	v_mfma_f32_16x16x32_bf16 v[26:29], v[138:141], v[204:207], v[26:29]
	v_mfma_f32_16x16x32_bf16 v[14:17], v[130:133], v[212:215], v[14:17]
	v_mfma_f32_16x16x32_bf16 v[10:13], v[138:141], v[212:215], v[10:13]
	v_mfma_f32_16x16x32_bf16 v[62:65], v[134:137], v[188:191], v[62:65]
	v_mfma_f32_16x16x32_bf16 v[58:61], v[142:145], v[188:191], v[58:61]
	v_mfma_f32_16x16x32_bf16 v[46:49], v[134:137], v[196:199], v[46:49]
	v_mfma_f32_16x16x32_bf16 v[42:45], v[142:145], v[196:199], v[42:45]
	v_mfma_f32_16x16x32_bf16 v[30:33], v[134:137], v[208:211], v[30:33]
	v_mfma_f32_16x16x32_bf16 v[26:29], v[142:145], v[208:211], v[26:29]
	v_mfma_f32_16x16x32_bf16 v[14:17], v[134:137], v[216:219], v[14:17]
	v_mfma_f32_16x16x32_bf16 v[10:13], v[142:145], v[216:219], v[10:13]
	v_mfma_f32_16x16x32_bf16 v[54:57], v[146:149], v[184:187], v[54:57]
	v_mfma_f32_16x16x32_bf16 v[50:53], v[154:157], v[184:187], v[50:53]
	v_mfma_f32_16x16x32_bf16 v[38:41], v[146:149], v[192:195], v[38:41]
	v_mfma_f32_16x16x32_bf16 v[34:37], v[154:157], v[192:195], v[34:37]
	v_mfma_f32_16x16x32_bf16 v[22:25], v[146:149], v[204:207], v[22:25]
	v_mfma_f32_16x16x32_bf16 v[18:21], v[154:157], v[204:207], v[18:21]
	v_mfma_f32_16x16x32_bf16 v[6:9], v[146:149], v[212:215], v[6:9]
	v_mfma_f32_16x16x32_bf16 v[2:5], v[154:157], v[212:215], v[2:5]
	v_mfma_f32_16x16x32_bf16 v[54:57], v[150:153], v[188:191], v[54:57]
	v_mfma_f32_16x16x32_bf16 v[50:53], v[180:183], v[188:191], v[50:53]
	v_mfma_f32_16x16x32_bf16 v[38:41], v[150:153], v[196:199], v[38:41]
	v_mfma_f32_16x16x32_bf16 v[34:37], v[180:183], v[196:199], v[34:37]
	v_mfma_f32_16x16x32_bf16 v[22:25], v[150:153], v[208:211], v[22:25]
	v_mfma_f32_16x16x32_bf16 v[18:21], v[180:183], v[208:211], v[18:21]
	v_mfma_f32_16x16x32_bf16 v[6:9], v[150:153], v[216:219], v[6:9]
	v_mfma_f32_16x16x32_bf16 v[2:5], v[180:183], v[216:219], v[2:5]
	s_setprio 0
	s_barrier
	s_add_i32 s50, s50, 2
	s_add_u32 s28, s28, 0x100
	s_addc_u32 s29, s29, 0
	s_add_u32 s25, s25, 0x100
	s_addc_u32 s27, s27, 0
	s_cmp_gt_u32 s50, 13
	s_cbranch_scc0 .LBB0_973
	s_and_b64 vcc, exec, s[14:15]
	s_cbranch_vccz .LBB0_976
	s_barrier

.LBB0_1097:
	s_add_u32 s28, s26, 0xfffc0080
	s_addc_u32 s29, s27, -1
	s_add_i32 s59, 0, 0x10000
	s_cmp_eq_u32 s58, 12
	s_cselect_b32 s31, s19, s29
	s_cselect_b32 s30, s25, s28
	v_add_u32_e32 v140, s59, v143
	s_cselect_b32 s29, s17, s57
	s_cselect_b32 s28, s53, s56
	s_add_i32 s60, 0, 0x14000
	ds_read_b128 v[150:153], v140
	ds_read_b128 v[154:157], v140 offset:1024
	ds_read_b128 v[158:161], v140 offset:2048
	ds_read_b128 v[162:165], v140 offset:3072
	v_add_u32_e32 v140, s60, v143
	ds_read_b128 v[166:169], v140
	ds_read_b128 v[180:183], v140 offset:1024
	ds_read_b128 v[184:187], v140 offset:2048
	ds_read_b128 v[188:191], v140 offset:3072
	v_lshl_add_u64 v[140:141], s[26:27], 0, v[136:137]
	s_add_i32 m0, s41, 0xc000
	ds_read_b128 v[192:195], v149
	ds_read_b128 v[196:199], v149 offset:1024
	ds_read_b128 v[200:203], v149 offset:2048
	ds_read_b128 v[204:207], v149 offset:3072
	ds_read_b128 v[208:211], v149 offset:4096
	ds_read_b128 v[212:215], v149 offset:5120
	ds_read_b128 v[216:219], v149 offset:6144
	ds_read_b128 v[236:239], v149 offset:7168
	global_load_lds_dwordx4 v[140:141], off
	v_lshl_add_u64 v[140:141], s[26:27], 0, v[138:139]
	s_add_i32 m0, s41, 0xe000
	s_nop 0
	global_load_lds_dwordx4 v[140:141], off
	s_waitcnt vmcnt(8)
	s_waitcnt lgkmcnt(0)
	s_barrier
	s_setprio 1
	v_mfma_f32_16x16x32_bf16 v[126:129], v[150:153], v[192:195], v[126:129]
	v_mfma_f32_16x16x32_bf16 v[118:121], v[158:161], v[192:195], v[118:121]
	v_mfma_f32_16x16x32_bf16 v[110:113], v[150:153], v[200:203], v[110:113]
	v_mfma_f32_16x16x32_bf16 v[102:105], v[158:161], v[200:203], v[102:105]
	v_mfma_f32_16x16x32_bf16 v[94:97], v[150:153], v[208:211], v[94:97]
	v_mfma_f32_16x16x32_bf16 v[86:89], v[158:161], v[208:211], v[86:89]
	v_mfma_f32_16x16x32_bf16 v[78:81], v[150:153], v[216:219], v[78:81]
	v_mfma_f32_16x16x32_bf16 v[70:73], v[158:161], v[216:219], v[70:73]
	v_mfma_f32_16x16x32_bf16 v[126:129], v[154:157], v[196:199], v[126:129]
	v_mfma_f32_16x16x32_bf16 v[118:121], v[162:165], v[196:199], v[118:121]
	v_mfma_f32_16x16x32_bf16 v[110:113], v[154:157], v[204:207], v[110:113]
	v_mfma_f32_16x16x32_bf16 v[102:105], v[162:165], v[204:207], v[102:105]
	v_mfma_f32_16x16x32_bf16 v[94:97], v[154:157], v[212:215], v[94:97]
	v_mfma_f32_16x16x32_bf16 v[86:89], v[162:165], v[212:215], v[86:89]
	v_mfma_f32_16x16x32_bf16 v[78:81], v[154:157], v[236:239], v[78:81]
	v_mfma_f32_16x16x32_bf16 v[70:73], v[162:165], v[236:239], v[70:73]
	v_mfma_f32_16x16x32_bf16 v[122:125], v[166:169], v[192:195], v[122:125]
	v_mfma_f32_16x16x32_bf16 v[114:117], v[184:187], v[192:195], v[114:117]
	v_mfma_f32_16x16x32_bf16 v[106:109], v[166:169], v[200:203], v[106:109]
	v_mfma_f32_16x16x32_bf16 v[98:101], v[184:187], v[200:203], v[98:101]
	v_mfma_f32_16x16x32_bf16 v[90:93], v[166:169], v[208:211], v[90:93]
	v_mfma_f32_16x16x32_bf16 v[82:85], v[184:187], v[208:211], v[82:85]
	v_mfma_f32_16x16x32_bf16 v[74:77], v[166:169], v[216:219], v[74:77]
	v_mfma_f32_16x16x32_bf16 v[66:69], v[184:187], v[216:219], v[66:69]
	v_mfma_f32_16x16x32_bf16 v[122:125], v[180:183], v[196:199], v[122:125]
	v_mfma_f32_16x16x32_bf16 v[114:117], v[188:191], v[196:199], v[114:117]
	v_mfma_f32_16x16x32_bf16 v[106:109], v[180:183], v[204:207], v[106:109]
	v_mfma_f32_16x16x32_bf16 v[98:101], v[188:191], v[204:207], v[98:101]
	v_mfma_f32_16x16x32_bf16 v[90:93], v[180:183], v[212:215], v[90:93]
	v_mfma_f32_16x16x32_bf16 v[82:85], v[188:191], v[212:215], v[82:85]
	v_mfma_f32_16x16x32_bf16 v[74:77], v[180:183], v[236:239], v[74:77]
	v_mfma_f32_16x16x32_bf16 v[66:69], v[188:191], v[236:239], v[66:69]
	s_setprio 0
	s_barrier
	s_add_i32 s59, s59, s38
	v_lshl_add_u64 v[140:141], s[28:29], 0, v[0:1]
	s_mov_b32 m0, s59
	ds_read_b128 v[192:195], v149 offset:16384
	ds_read_b128 v[196:199], v149 offset:17408
	ds_read_b128 v[200:203], v149 offset:18432
	ds_read_b128 v[204:207], v149 offset:19456
	ds_read_b128 v[208:211], v149 offset:20480
	ds_read_b128 v[212:215], v149 offset:21504
	ds_read_b128 v[216:219], v149 offset:22528
	ds_read_b128 v[236:239], v149 offset:23552
	global_load_lds_dwordx4 v[140:141], off
	s_add_i32 m0, s59, 0x2000
	s_add_u32 s64, s28, 0x40000
	v_lshl_add_u64 v[222:223], s[28:29], 0, v[130:131]
	s_addc_u32 s65, s29, 0
	s_add_i32 s59, s60, s38
	global_load_lds_dwordx4 v[222:223], off
	v_lshl_add_u64 v[232:233], s[64:65], 0, v[0:1]
	s_mov_b32 m0, s59
	v_lshl_add_u64 v[240:241], s[30:31], 0, v[132:133]
	global_load_lds_dwordx4 v[232:233], off
	v_lshl_add_u64 v[232:233], s[64:65], 0, v[130:131]
	s_add_i32 m0, s59, 0x2000
	s_nop 0
	global_load_lds_dwordx4 v[232:233], off
	v_lshl_add_u64 v[232:233], s[30:31], 0, v[134:135]
	s_mov_b32 m0, s41
	s_nop 0
	global_load_lds_dwordx4 v[232:233], off
	s_mov_b32 m0, s42
	s_nop 0
	global_load_lds_dwordx4 v[240:241], off
	s_waitcnt vmcnt(8)
	s_waitcnt lgkmcnt(0)
	s_barrier
	s_setprio 1
	v_mfma_f32_16x16x32_bf16 v[62:65], v[150:153], v[192:195], v[62:65]
	v_mfma_f32_16x16x32_bf16 v[54:57], v[158:161], v[192:195], v[54:57]
	v_mfma_f32_16x16x32_bf16 v[46:49], v[150:153], v[200:203], v[46:49]
	v_mfma_f32_16x16x32_bf16 v[38:41], v[158:161], v[200:203], v[38:41]
	v_mfma_f32_16x16x32_bf16 v[30:33], v[150:153], v[208:211], v[30:33]
	v_mfma_f32_16x16x32_bf16 v[22:25], v[158:161], v[208:211], v[22:25]
	v_mfma_f32_16x16x32_bf16 v[14:17], v[150:153], v[216:219], v[14:17]
	v_mfma_f32_16x16x32_bf16 v[6:9], v[158:161], v[216:219], v[6:9]
	v_mfma_f32_16x16x32_bf16 v[62:65], v[154:157], v[196:199], v[62:65]
	v_mfma_f32_16x16x32_bf16 v[54:57], v[162:165], v[196:199], v[54:57]
	v_mfma_f32_16x16x32_bf16 v[46:49], v[154:157], v[204:207], v[46:49]
	v_mfma_f32_16x16x32_bf16 v[38:41], v[162:165], v[204:207], v[38:41]
	v_mfma_f32_16x16x32_bf16 v[30:33], v[154:157], v[212:215], v[30:33]
	v_mfma_f32_16x16x32_bf16 v[22:25], v[162:165], v[212:215], v[22:25]
	v_mfma_f32_16x16x32_bf16 v[14:17], v[154:157], v[236:239], v[14:17]
	v_mfma_f32_16x16x32_bf16 v[6:9], v[162:165], v[236:239], v[6:9]
	v_mfma_f32_16x16x32_bf16 v[58:61], v[166:169], v[192:195], v[58:61]
	v_mfma_f32_16x16x32_bf16 v[50:53], v[184:187], v[192:195], v[50:53]
	v_mfma_f32_16x16x32_bf16 v[42:45], v[166:169], v[200:203], v[42:45]
	v_mfma_f32_16x16x32_bf16 v[34:37], v[184:187], v[200:203], v[34:37]
	v_mfma_f32_16x16x32_bf16 v[26:29], v[166:169], v[208:211], v[26:29]
	v_mfma_f32_16x16x32_bf16 v[18:21], v[184:187], v[208:211], v[18:21]
	v_mfma_f32_16x16x32_bf16 v[10:13], v[166:169], v[216:219], v[10:13]
	v_mfma_f32_16x16x32_bf16 v[2:5], v[184:187], v[216:219], v[2:5]
	v_mfma_f32_16x16x32_bf16 v[58:61], v[180:183], v[196:199], v[58:61]
	v_mfma_f32_16x16x32_bf16 v[50:53], v[188:191], v[196:199], v[50:53]
	v_mfma_f32_16x16x32_bf16 v[42:45], v[180:183], v[204:207], v[42:45]
	v_mfma_f32_16x16x32_bf16 v[34:37], v[188:191], v[204:207], v[34:37]
	v_mfma_f32_16x16x32_bf16 v[26:29], v[180:183], v[212:215], v[26:29]
	v_mfma_f32_16x16x32_bf16 v[18:21], v[188:191], v[212:215], v[18:21]
	v_mfma_f32_16x16x32_bf16 v[10:13], v[180:183], v[236:239], v[10:13]
	v_mfma_f32_16x16x32_bf16 v[2:5], v[188:191], v[236:239], v[2:5]
	s_setprio 0
	s_barrier
	s_add_i32 s59, 0, 0x18000
	s_add_i32 s60, 0, 0x1c000
	v_add_u32_e32 v162, s59, v143
	v_add_u32_e32 v188, s60, v143
	ds_read_b128 v[150:153], v162
	ds_read_b128 v[154:157], v162 offset:1024
	ds_read_b128 v[158:161], v162 offset:2048
	ds_read_b128 v[162:165], v162 offset:3072
	ds_read_b128 v[166:169], v188
	ds_read_b128 v[180:183], v188 offset:1024
	ds_read_b128 v[184:187], v188 offset:2048
	ds_read_b128 v[188:191], v188 offset:3072
	s_add_u32 s30, s30, 0x40000
	s_addc_u32 s31, s31, 0
	s_mov_b32 m0, s43
	v_lshl_add_u64 v[242:243], s[30:31], 0, v[134:135]
	ds_read_b128 v[192:195], v149 offset:32768
	ds_read_b128 v[196:199], v149 offset:33792
	ds_read_b128 v[200:203], v149 offset:34816
	ds_read_b128 v[204:207], v149 offset:35840
	ds_read_b128 v[208:211], v149 offset:36864
	ds_read_b128 v[212:215], v149 offset:37888
	ds_read_b128 v[216:219], v149 offset:38912
	ds_read_b128 v[236:239], v149 offset:39936
	global_load_lds_dwordx4 v[242:243], off
	v_lshl_add_u64 v[242:243], s[30:31], 0, v[132:133]
	s_mov_b32 m0, s46
	s_nop 0
	global_load_lds_dwordx4 v[242:243], off
	s_waitcnt vmcnt(8)
	s_waitcnt lgkmcnt(0)
	s_barrier
	s_setprio 1
	v_mfma_f32_16x16x32_bf16 v[126:129], v[150:153], v[192:195], v[126:129]
	v_mfma_f32_16x16x32_bf16 v[118:121], v[158:161], v[192:195], v[118:121]
	v_mfma_f32_16x16x32_bf16 v[110:113], v[150:153], v[200:203], v[110:113]
	v_mfma_f32_16x16x32_bf16 v[102:105], v[158:161], v[200:203], v[102:105]
	v_mfma_f32_16x16x32_bf16 v[94:97], v[150:153], v[208:211], v[94:97]
	v_mfma_f32_16x16x32_bf16 v[86:89], v[158:161], v[208:211], v[86:89]
	v_mfma_f32_16x16x32_bf16 v[78:81], v[150:153], v[216:219], v[78:81]
	v_mfma_f32_16x16x32_bf16 v[70:73], v[158:161], v[216:219], v[70:73]
	v_mfma_f32_16x16x32_bf16 v[126:129], v[154:157], v[196:199], v[126:129]
	v_mfma_f32_16x16x32_bf16 v[118:121], v[162:165], v[196:199], v[118:121]
	v_mfma_f32_16x16x32_bf16 v[110:113], v[154:157], v[204:207], v[110:113]
	v_mfma_f32_16x16x32_bf16 v[102:105], v[162:165], v[204:207], v[102:105]
	v_mfma_f32_16x16x32_bf16 v[94:97], v[154:157], v[212:215], v[94:97]
	v_mfma_f32_16x16x32_bf16 v[86:89], v[162:165], v[212:215], v[86:89]
	v_mfma_f32_16x16x32_bf16 v[78:81], v[154:157], v[236:239], v[78:81]
	v_mfma_f32_16x16x32_bf16 v[70:73], v[162:165], v[236:239], v[70:73]
	v_mfma_f32_16x16x32_bf16 v[122:125], v[166:169], v[192:195], v[122:125]
	v_mfma_f32_16x16x32_bf16 v[114:117], v[184:187], v[192:195], v[114:117]
	v_mfma_f32_16x16x32_bf16 v[106:109], v[166:169], v[200:203], v[106:109]
	v_mfma_f32_16x16x32_bf16 v[98:101], v[184:187], v[200:203], v[98:101]
	v_mfma_f32_16x16x32_bf16 v[90:93], v[166:169], v[208:211], v[90:93]
	v_mfma_f32_16x16x32_bf16 v[82:85], v[184:187], v[208:211], v[82:85]
	v_mfma_f32_16x16x32_bf16 v[74:77], v[166:169], v[216:219], v[74:77]
	v_mfma_f32_16x16x32_bf16 v[66:69], v[184:187], v[216:219], v[66:69]
	v_mfma_f32_16x16x32_bf16 v[122:125], v[180:183], v[196:199], v[122:125]
	v_mfma_f32_16x16x32_bf16 v[114:117], v[188:191], v[196:199], v[114:117]
	v_mfma_f32_16x16x32_bf16 v[106:109], v[180:183], v[204:207], v[106:109]
	v_mfma_f32_16x16x32_bf16 v[98:101], v[188:191], v[204:207], v[98:101]
	v_mfma_f32_16x16x32_bf16 v[90:93], v[180:183], v[212:215], v[90:93]
	v_mfma_f32_16x16x32_bf16 v[82:85], v[188:191], v[212:215], v[82:85]
	v_mfma_f32_16x16x32_bf16 v[74:77], v[180:183], v[236:239], v[74:77]
	v_mfma_f32_16x16x32_bf16 v[66:69], v[188:191], v[236:239], v[66:69]
	s_setprio 0
	s_barrier
	s_add_i32 s30, s59, s38
	v_lshl_add_u64 v[140:141], v[140:141], 0, s[54:55]
	s_mov_b32 m0, s30
	ds_read_b128 v[192:195], v149 offset:49152
	ds_read_b128 v[196:199], v149 offset:50176
	ds_read_b128 v[200:203], v149 offset:51200
	ds_read_b128 v[204:207], v149 offset:52224
	ds_read_b128 v[208:211], v149 offset:53248
	ds_read_b128 v[212:215], v149 offset:54272
	ds_read_b128 v[216:219], v149 offset:55296
	ds_read_b128 v[236:239], v149 offset:56320
	global_load_lds_dwordx4 v[140:141], off
	s_add_i32 m0, s30, 0x2000
	s_add_u32 s28, s28, 0x40080
	v_lshl_add_u64 v[140:141], v[222:223], 0, s[54:55]
	s_addc_u32 s29, s29, 0
	s_add_i32 s30, s60, s38
	global_load_lds_dwordx4 v[140:141], off
	v_lshl_add_u64 v[140:141], s[28:29], 0, v[0:1]
	s_mov_b32 m0, s30
	s_nop 0
	global_load_lds_dwordx4 v[140:141], off
	v_lshl_add_u64 v[140:141], s[28:29], 0, v[130:131]
	s_add_i32 m0, s30, 0x2000
	s_nop 0
	global_load_lds_dwordx4 v[140:141], off
	v_lshl_add_u64 v[140:141], v[232:233], 0, s[54:55]
	s_mov_b32 m0, s47
	s_nop 0
	global_load_lds_dwordx4 v[140:141], off
	v_lshl_add_u64 v[140:141], v[240:241], 0, s[54:55]
	s_mov_b32 m0, s50
	s_nop 0
	global_load_lds_dwordx4 v[140:141], off
	s_waitcnt vmcnt(8)
	s_waitcnt lgkmcnt(0)
	s_barrier
	s_setprio 1
	v_mfma_f32_16x16x32_bf16 v[62:65], v[150:153], v[192:195], v[62:65]
	v_mfma_f32_16x16x32_bf16 v[54:57], v[158:161], v[192:195], v[54:57]
	v_mfma_f32_16x16x32_bf16 v[46:49], v[150:153], v[200:203], v[46:49]
	v_mfma_f32_16x16x32_bf16 v[38:41], v[158:161], v[200:203], v[38:41]
	v_mfma_f32_16x16x32_bf16 v[30:33], v[150:153], v[208:211], v[30:33]
	v_mfma_f32_16x16x32_bf16 v[22:25], v[158:161], v[208:211], v[22:25]
	v_mfma_f32_16x16x32_bf16 v[14:17], v[150:153], v[216:219], v[14:17]
	v_mfma_f32_16x16x32_bf16 v[6:9], v[158:161], v[216:219], v[6:9]
	v_mfma_f32_16x16x32_bf16 v[62:65], v[154:157], v[196:199], v[62:65]
	v_mfma_f32_16x16x32_bf16 v[54:57], v[162:165], v[196:199], v[54:57]
	v_mfma_f32_16x16x32_bf16 v[46:49], v[154:157], v[204:207], v[46:49]
	v_mfma_f32_16x16x32_bf16 v[38:41], v[162:165], v[204:207], v[38:41]
	v_mfma_f32_16x16x32_bf16 v[30:33], v[154:157], v[212:215], v[30:33]
	v_mfma_f32_16x16x32_bf16 v[22:25], v[162:165], v[212:215], v[22:25]
	v_mfma_f32_16x16x32_bf16 v[14:17], v[154:157], v[236:239], v[14:17]
	v_mfma_f32_16x16x32_bf16 v[6:9], v[162:165], v[236:239], v[6:9]
	v_mfma_f32_16x16x32_bf16 v[58:61], v[166:169], v[192:195], v[58:61]
	v_mfma_f32_16x16x32_bf16 v[50:53], v[184:187], v[192:195], v[50:53]
	v_mfma_f32_16x16x32_bf16 v[42:45], v[166:169], v[200:203], v[42:45]
	v_mfma_f32_16x16x32_bf16 v[34:37], v[184:187], v[200:203], v[34:37]
	v_mfma_f32_16x16x32_bf16 v[26:29], v[166:169], v[208:211], v[26:29]
	v_mfma_f32_16x16x32_bf16 v[18:21], v[184:187], v[208:211], v[18:21]
	v_mfma_f32_16x16x32_bf16 v[10:13], v[166:169], v[216:219], v[10:13]
	v_mfma_f32_16x16x32_bf16 v[2:5], v[184:187], v[216:219], v[2:5]
	v_mfma_f32_16x16x32_bf16 v[58:61], v[180:183], v[196:199], v[58:61]
	v_mfma_f32_16x16x32_bf16 v[50:53], v[188:191], v[196:199], v[50:53]
	v_mfma_f32_16x16x32_bf16 v[42:45], v[180:183], v[204:207], v[42:45]
	v_mfma_f32_16x16x32_bf16 v[34:37], v[188:191], v[204:207], v[34:37]
	v_mfma_f32_16x16x32_bf16 v[26:29], v[180:183], v[212:215], v[26:29]
	v_mfma_f32_16x16x32_bf16 v[18:21], v[188:191], v[212:215], v[18:21]
	v_mfma_f32_16x16x32_bf16 v[10:13], v[180:183], v[236:239], v[10:13]
	v_mfma_f32_16x16x32_bf16 v[2:5], v[188:191], v[236:239], v[2:5]
	s_setprio 0
	s_barrier
	s_add_i32 s58, s58, 2
	s_add_u32 s26, s26, 0x100
	s_addc_u32 s27, s27, 0
	s_add_u32 s56, s56, 0x100
	s_addc_u32 s57, s57, 0
	s_cmp_gt_u32 s58, 13
	s_cbranch_scc0 .LBB0_1097
	s_and_b64 vcc, exec, s[14:15]
	s_cbranch_vccz .LBB0_1100
	s_barrier

.LBB0_1197:
	s_add_u32 s8, s30, 0x100
	s_addc_u32 s9, s31, 0
	s_add_i32 s53, 0, 0x10000
	s_cmp_eq_u32 s29, 40
	s_cselect_b32 s37, s25, s9
	s_cselect_b32 s36, s24, s8
	s_cselect_b32 s35, s27, s3
	s_cselect_b32 s34, s26, s2
	s_add_i32 s60, 0, 0x14000
	v_add_u32_e32 v142, s53, v204
	v_add_u32_e32 v180, s60, v204
	ds_read_b128 v[130:133], v142
	ds_read_b128 v[134:137], v142 offset:1024
	ds_read_b128 v[138:141], v142 offset:2048
	ds_read_b128 v[142:145], v142 offset:3072
	ds_read_b128 v[146:149], v180
	ds_read_b128 v[150:153], v180 offset:1024
	ds_read_b128 v[154:157], v180 offset:2048
	ds_read_b128 v[180:183], v180 offset:3072
	v_lshl_add_u64 v[222:223], s[30:31], 0, v[166:167]
	s_add_i32 m0, s46, 0xc000
	ds_read_b128 v[184:187], v206
	ds_read_b128 v[188:191], v206 offset:1024
	ds_read_b128 v[192:195], v206 offset:2048
	ds_read_b128 v[196:199], v206 offset:3072
	ds_read_b128 v[200:203], v206 offset:4096
	ds_read_b128 v[208:211], v206 offset:5120
	ds_read_b128 v[212:215], v206 offset:6144
	ds_read_b128 v[216:219], v206 offset:7168
	global_load_lds_dwordx4 v[222:223], off
	v_lshl_add_u64 v[222:223], s[30:31], 0, v[168:169]
	s_add_i32 m0, s46, 0xe000
	s_nop 0
	global_load_lds_dwordx4 v[222:223], off
	s_waitcnt vmcnt(8)
	s_waitcnt lgkmcnt(0)
	s_barrier
	s_setprio 1
	v_mfma_f32_16x16x32_bf16 v[126:129], v[130:133], v[184:187], v[126:129]
	v_mfma_f32_16x16x32_bf16 v[122:125], v[138:141], v[184:187], v[122:125]
	v_mfma_f32_16x16x32_bf16 v[110:113], v[130:133], v[192:195], v[110:113]
	v_mfma_f32_16x16x32_bf16 v[106:109], v[138:141], v[192:195], v[106:109]
	v_mfma_f32_16x16x32_bf16 v[94:97], v[130:133], v[200:203], v[94:97]
	v_mfma_f32_16x16x32_bf16 v[90:93], v[138:141], v[200:203], v[90:93]
	v_mfma_f32_16x16x32_bf16 v[78:81], v[130:133], v[212:215], v[78:81]
	v_mfma_f32_16x16x32_bf16 v[74:77], v[138:141], v[212:215], v[74:77]
	v_mfma_f32_16x16x32_bf16 v[126:129], v[134:137], v[188:191], v[126:129]
	v_mfma_f32_16x16x32_bf16 v[122:125], v[142:145], v[188:191], v[122:125]
	v_mfma_f32_16x16x32_bf16 v[110:113], v[134:137], v[196:199], v[110:113]
	v_mfma_f32_16x16x32_bf16 v[106:109], v[142:145], v[196:199], v[106:109]
	v_mfma_f32_16x16x32_bf16 v[94:97], v[134:137], v[208:211], v[94:97]
	v_mfma_f32_16x16x32_bf16 v[90:93], v[142:145], v[208:211], v[90:93]
	v_mfma_f32_16x16x32_bf16 v[78:81], v[134:137], v[216:219], v[78:81]
	v_mfma_f32_16x16x32_bf16 v[74:77], v[142:145], v[216:219], v[74:77]
	v_mfma_f32_16x16x32_bf16 v[118:121], v[146:149], v[184:187], v[118:121]
	v_mfma_f32_16x16x32_bf16 v[114:117], v[154:157], v[184:187], v[114:117]
	v_mfma_f32_16x16x32_bf16 v[102:105], v[146:149], v[192:195], v[102:105]
	v_mfma_f32_16x16x32_bf16 v[98:101], v[154:157], v[192:195], v[98:101]
	v_mfma_f32_16x16x32_bf16 v[86:89], v[146:149], v[200:203], v[86:89]
	v_mfma_f32_16x16x32_bf16 v[82:85], v[154:157], v[200:203], v[82:85]
	v_mfma_f32_16x16x32_bf16 v[70:73], v[146:149], v[212:215], v[70:73]
	v_mfma_f32_16x16x32_bf16 v[66:69], v[154:157], v[212:215], v[66:69]
	v_mfma_f32_16x16x32_bf16 v[118:121], v[150:153], v[188:191], v[118:121]
	v_mfma_f32_16x16x32_bf16 v[114:117], v[180:183], v[188:191], v[114:117]
	v_mfma_f32_16x16x32_bf16 v[102:105], v[150:153], v[196:199], v[102:105]
	v_mfma_f32_16x16x32_bf16 v[98:101], v[180:183], v[196:199], v[98:101]
	v_mfma_f32_16x16x32_bf16 v[86:89], v[150:153], v[208:211], v[86:89]
	v_mfma_f32_16x16x32_bf16 v[82:85], v[180:183], v[208:211], v[82:85]
	v_mfma_f32_16x16x32_bf16 v[70:73], v[150:153], v[216:219], v[70:73]
	v_mfma_f32_16x16x32_bf16 v[66:69], v[180:183], v[216:219], v[66:69]
	s_setprio 0
	s_barrier
	s_add_i32 s30, s53, s40
	v_lshl_add_u64 v[222:223], s[34:35], 0, v[0:1]
	s_mov_b32 m0, s30
	ds_read_b128 v[184:187], v206 offset:16384
	ds_read_b128 v[188:191], v206 offset:17408
	ds_read_b128 v[192:195], v206 offset:18432
	ds_read_b128 v[196:199], v206 offset:19456
	ds_read_b128 v[200:203], v206 offset:20480
	ds_read_b128 v[208:211], v206 offset:21504
	ds_read_b128 v[212:215], v206 offset:22528
	ds_read_b128 v[216:219], v206 offset:23552
	global_load_lds_dwordx4 v[222:223], off
	s_add_i32 m0, s30, 0x2000
	s_add_u32 s30, s34, 0xb0000
	v_lshl_add_u64 v[232:233], s[34:35], 0, v[162:163]
	s_addc_u32 s31, s35, 0
	s_add_i32 s53, s60, s40
	global_load_lds_dwordx4 v[232:233], off
	v_lshl_add_u64 v[236:237], s[30:31], 0, v[0:1]
	s_mov_b32 m0, s53
	v_lshl_add_u64 v[238:239], s[36:37], 0, v[160:161]
	global_load_lds_dwordx4 v[236:237], off
	v_lshl_add_u64 v[236:237], s[30:31], 0, v[162:163]
	s_add_i32 m0, s53, 0x2000
	s_nop 0
	global_load_lds_dwordx4 v[236:237], off
	v_lshl_add_u64 v[236:237], s[36:37], 0, v[158:159]
	s_mov_b32 m0, s46
	s_nop 0
	global_load_lds_dwordx4 v[236:237], off
	s_mov_b32 m0, s47
	s_nop 0
	global_load_lds_dwordx4 v[238:239], off
	s_waitcnt vmcnt(8)
	s_waitcnt lgkmcnt(0)
	s_barrier
	s_setprio 1
	v_mfma_f32_16x16x32_bf16 v[62:65], v[130:133], v[184:187], v[62:65]
	v_mfma_f32_16x16x32_bf16 v[58:61], v[138:141], v[184:187], v[58:61]
	v_mfma_f32_16x16x32_bf16 v[46:49], v[130:133], v[192:195], v[46:49]
	v_mfma_f32_16x16x32_bf16 v[42:45], v[138:141], v[192:195], v[42:45]
	v_mfma_f32_16x16x32_bf16 v[30:33], v[130:133], v[200:203], v[30:33]
	v_mfma_f32_16x16x32_bf16 v[26:29], v[138:141], v[200:203], v[26:29]
	v_mfma_f32_16x16x32_bf16 v[14:17], v[130:133], v[212:215], v[14:17]
	v_mfma_f32_16x16x32_bf16 v[10:13], v[138:141], v[212:215], v[10:13]
	v_mfma_f32_16x16x32_bf16 v[62:65], v[134:137], v[188:191], v[62:65]
	v_mfma_f32_16x16x32_bf16 v[58:61], v[142:145], v[188:191], v[58:61]
	v_mfma_f32_16x16x32_bf16 v[46:49], v[134:137], v[196:199], v[46:49]
	v_mfma_f32_16x16x32_bf16 v[42:45], v[142:145], v[196:199], v[42:45]
	v_mfma_f32_16x16x32_bf16 v[30:33], v[134:137], v[208:211], v[30:33]
	v_mfma_f32_16x16x32_bf16 v[26:29], v[142:145], v[208:211], v[26:29]
	v_mfma_f32_16x16x32_bf16 v[14:17], v[134:137], v[216:219], v[14:17]
	v_mfma_f32_16x16x32_bf16 v[10:13], v[142:145], v[216:219], v[10:13]
	v_mfma_f32_16x16x32_bf16 v[54:57], v[146:149], v[184:187], v[54:57]
	v_mfma_f32_16x16x32_bf16 v[50:53], v[154:157], v[184:187], v[50:53]
	v_mfma_f32_16x16x32_bf16 v[38:41], v[146:149], v[192:195], v[38:41]
	v_mfma_f32_16x16x32_bf16 v[34:37], v[154:157], v[192:195], v[34:37]
	v_mfma_f32_16x16x32_bf16 v[22:25], v[146:149], v[200:203], v[22:25]
	v_mfma_f32_16x16x32_bf16 v[18:21], v[154:157], v[200:203], v[18:21]
	v_mfma_f32_16x16x32_bf16 v[6:9], v[146:149], v[212:215], v[6:9]
	v_mfma_f32_16x16x32_bf16 v[2:5], v[154:157], v[212:215], v[2:5]
	v_mfma_f32_16x16x32_bf16 v[54:57], v[150:153], v[188:191], v[54:57]
	v_mfma_f32_16x16x32_bf16 v[50:53], v[180:183], v[188:191], v[50:53]
	v_mfma_f32_16x16x32_bf16 v[38:41], v[150:153], v[196:199], v[38:41]
	v_mfma_f32_16x16x32_bf16 v[34:37], v[180:183], v[196:199], v[34:37]
	v_mfma_f32_16x16x32_bf16 v[22:25], v[150:153], v[208:211], v[22:25]
	v_mfma_f32_16x16x32_bf16 v[18:21], v[180:183], v[208:211], v[18:21]
	v_mfma_f32_16x16x32_bf16 v[6:9], v[150:153], v[216:219], v[6:9]
	v_mfma_f32_16x16x32_bf16 v[2:5], v[180:183], v[216:219], v[2:5]
	s_setprio 0
	s_barrier
	s_add_i32 s53, 0, 0x18000
	s_add_i32 s60, 0, 0x1c000
	v_add_u32_e32 v142, s53, v204
	v_add_u32_e32 v180, s60, v204
	ds_read_b128 v[130:133], v142
	ds_read_b128 v[134:137], v142 offset:1024
	ds_read_b128 v[138:141], v142 offset:2048
	ds_read_b128 v[142:145], v142 offset:3072
	ds_read_b128 v[146:149], v180
	ds_read_b128 v[150:153], v180 offset:1024
	ds_read_b128 v[154:157], v180 offset:2048
	ds_read_b128 v[180:183], v180 offset:3072
	s_add_u32 s30, s36, 0xb0000
	s_addc_u32 s31, s37, 0
	s_mov_b32 m0, s52
	v_lshl_add_u64 v[240:241], s[30:31], 0, v[158:159]
	ds_read_b128 v[184:187], v206 offset:32768
	ds_read_b128 v[188:191], v206 offset:33792
	ds_read_b128 v[192:195], v206 offset:34816
	ds_read_b128 v[196:199], v206 offset:35840
	ds_read_b128 v[200:203], v206 offset:36864
	ds_read_b128 v[208:211], v206 offset:37888
	ds_read_b128 v[212:215], v206 offset:38912
	ds_read_b128 v[216:219], v206 offset:39936
	global_load_lds_dwordx4 v[240:241], off
	v_lshl_add_u64 v[240:241], s[30:31], 0, v[160:161]
	s_mov_b32 m0, s56
	s_nop 0
	global_load_lds_dwordx4 v[240:241], off
	s_waitcnt vmcnt(8)
	s_waitcnt lgkmcnt(0)
	s_barrier
	s_setprio 1
	v_mfma_f32_16x16x32_bf16 v[126:129], v[130:133], v[184:187], v[126:129]
	v_mfma_f32_16x16x32_bf16 v[122:125], v[138:141], v[184:187], v[122:125]
	v_mfma_f32_16x16x32_bf16 v[110:113], v[130:133], v[192:195], v[110:113]
	v_mfma_f32_16x16x32_bf16 v[106:109], v[138:141], v[192:195], v[106:109]
	v_mfma_f32_16x16x32_bf16 v[94:97], v[130:133], v[200:203], v[94:97]
	v_mfma_f32_16x16x32_bf16 v[90:93], v[138:141], v[200:203], v[90:93]
	v_mfma_f32_16x16x32_bf16 v[78:81], v[130:133], v[212:215], v[78:81]
	v_mfma_f32_16x16x32_bf16 v[74:77], v[138:141], v[212:215], v[74:77]
	v_mfma_f32_16x16x32_bf16 v[126:129], v[134:137], v[188:191], v[126:129]
	v_mfma_f32_16x16x32_bf16 v[122:125], v[142:145], v[188:191], v[122:125]
	v_mfma_f32_16x16x32_bf16 v[110:113], v[134:137], v[196:199], v[110:113]
	v_mfma_f32_16x16x32_bf16 v[106:109], v[142:145], v[196:199], v[106:109]
	v_mfma_f32_16x16x32_bf16 v[94:97], v[134:137], v[208:211], v[94:97]
	v_mfma_f32_16x16x32_bf16 v[90:93], v[142:145], v[208:211], v[90:93]
	v_mfma_f32_16x16x32_bf16 v[78:81], v[134:137], v[216:219], v[78:81]
	v_mfma_f32_16x16x32_bf16 v[74:77], v[142:145], v[216:219], v[74:77]
	v_mfma_f32_16x16x32_bf16 v[118:121], v[146:149], v[184:187], v[118:121]
	v_mfma_f32_16x16x32_bf16 v[114:117], v[154:157], v[184:187], v[114:117]
	v_mfma_f32_16x16x32_bf16 v[102:105], v[146:149], v[192:195], v[102:105]
	v_mfma_f32_16x16x32_bf16 v[98:101], v[154:157], v[192:195], v[98:101]
	v_mfma_f32_16x16x32_bf16 v[86:89], v[146:149], v[200:203], v[86:89]
	v_mfma_f32_16x16x32_bf16 v[82:85], v[154:157], v[200:203], v[82:85]
	v_mfma_f32_16x16x32_bf16 v[70:73], v[146:149], v[212:215], v[70:73]
	v_mfma_f32_16x16x32_bf16 v[66:69], v[154:157], v[212:215], v[66:69]
	v_mfma_f32_16x16x32_bf16 v[118:121], v[150:153], v[188:191], v[118:121]
	v_mfma_f32_16x16x32_bf16 v[114:117], v[180:183], v[188:191], v[114:117]
	v_mfma_f32_16x16x32_bf16 v[102:105], v[150:153], v[196:199], v[102:105]
	v_mfma_f32_16x16x32_bf16 v[98:101], v[180:183], v[196:199], v[98:101]
	v_mfma_f32_16x16x32_bf16 v[86:89], v[150:153], v[208:211], v[86:89]
	v_mfma_f32_16x16x32_bf16 v[82:85], v[180:183], v[208:211], v[82:85]
	v_mfma_f32_16x16x32_bf16 v[70:73], v[150:153], v[216:219], v[70:73]
	v_mfma_f32_16x16x32_bf16 v[66:69], v[180:183], v[216:219], v[66:69]
	s_setprio 0
	s_barrier
	s_add_i32 s30, s53, s40
	v_lshl_add_u64 v[222:223], v[222:223], 0, s[54:55]
	s_mov_b32 m0, s30
	ds_read_b128 v[184:187], v206 offset:49152
	ds_read_b128 v[188:191], v206 offset:50176
	ds_read_b128 v[192:195], v206 offset:51200
	ds_read_b128 v[196:199], v206 offset:52224
	ds_read_b128 v[200:203], v206 offset:53248
	ds_read_b128 v[208:211], v206 offset:54272
	ds_read_b128 v[212:215], v206 offset:55296
	ds_read_b128 v[216:219], v206 offset:56320
	global_load_lds_dwordx4 v[222:223], off
	s_add_i32 m0, s30, 0x2000
	s_add_u32 s30, s34, 0xb0080
	v_lshl_add_u64 v[222:223], v[232:233], 0, s[54:55]
	s_addc_u32 s31, s35, 0
	s_add_i32 s34, s60, s40
	global_load_lds_dwordx4 v[222:223], off
	v_lshl_add_u64 v[222:223], s[30:31], 0, v[0:1]
	s_mov_b32 m0, s34
	s_nop 0
	global_load_lds_dwordx4 v[222:223], off
	v_lshl_add_u64 v[222:223], s[30:31], 0, v[162:163]
	s_add_i32 m0, s34, 0x2000
	s_nop 0
	global_load_lds_dwordx4 v[222:223], off
	v_lshl_add_u64 v[222:223], v[236:237], 0, s[54:55]
	s_mov_b32 m0, s58
	s_nop 0
	global_load_lds_dwordx4 v[222:223], off
	v_lshl_add_u64 v[222:223], v[238:239], 0, s[54:55]
	s_mov_b32 m0, s59
	s_nop 0
	global_load_lds_dwordx4 v[222:223], off
	s_waitcnt vmcnt(8)
	s_waitcnt lgkmcnt(0)
	s_barrier
	s_setprio 1
	v_mfma_f32_16x16x32_bf16 v[62:65], v[130:133], v[184:187], v[62:65]
	v_mfma_f32_16x16x32_bf16 v[58:61], v[138:141], v[184:187], v[58:61]
	v_mfma_f32_16x16x32_bf16 v[46:49], v[130:133], v[192:195], v[46:49]
	v_mfma_f32_16x16x32_bf16 v[42:45], v[138:141], v[192:195], v[42:45]
	v_mfma_f32_16x16x32_bf16 v[30:33], v[130:133], v[200:203], v[30:33]
	v_mfma_f32_16x16x32_bf16 v[26:29], v[138:141], v[200:203], v[26:29]
	v_mfma_f32_16x16x32_bf16 v[14:17], v[130:133], v[212:215], v[14:17]
	v_mfma_f32_16x16x32_bf16 v[10:13], v[138:141], v[212:215], v[10:13]
	v_mfma_f32_16x16x32_bf16 v[62:65], v[134:137], v[188:191], v[62:65]
	v_mfma_f32_16x16x32_bf16 v[58:61], v[142:145], v[188:191], v[58:61]
	v_mfma_f32_16x16x32_bf16 v[46:49], v[134:137], v[196:199], v[46:49]
	v_mfma_f32_16x16x32_bf16 v[42:45], v[142:145], v[196:199], v[42:45]
	v_mfma_f32_16x16x32_bf16 v[30:33], v[134:137], v[208:211], v[30:33]
	v_mfma_f32_16x16x32_bf16 v[26:29], v[142:145], v[208:211], v[26:29]
	v_mfma_f32_16x16x32_bf16 v[14:17], v[134:137], v[216:219], v[14:17]
	v_mfma_f32_16x16x32_bf16 v[10:13], v[142:145], v[216:219], v[10:13]
	v_mfma_f32_16x16x32_bf16 v[54:57], v[146:149], v[184:187], v[54:57]
	v_mfma_f32_16x16x32_bf16 v[50:53], v[154:157], v[184:187], v[50:53]
	v_mfma_f32_16x16x32_bf16 v[38:41], v[146:149], v[192:195], v[38:41]
	v_mfma_f32_16x16x32_bf16 v[34:37], v[154:157], v[192:195], v[34:37]
	v_mfma_f32_16x16x32_bf16 v[22:25], v[146:149], v[200:203], v[22:25]
	v_mfma_f32_16x16x32_bf16 v[18:21], v[154:157], v[200:203], v[18:21]
	v_mfma_f32_16x16x32_bf16 v[6:9], v[146:149], v[212:215], v[6:9]
	v_mfma_f32_16x16x32_bf16 v[2:5], v[154:157], v[212:215], v[2:5]
	v_mfma_f32_16x16x32_bf16 v[54:57], v[150:153], v[188:191], v[54:57]
	v_mfma_f32_16x16x32_bf16 v[50:53], v[180:183], v[188:191], v[50:53]
	v_mfma_f32_16x16x32_bf16 v[38:41], v[150:153], v[196:199], v[38:41]
	v_mfma_f32_16x16x32_bf16 v[34:37], v[180:183], v[196:199], v[34:37]
	v_mfma_f32_16x16x32_bf16 v[22:25], v[150:153], v[208:211], v[22:25]
	v_mfma_f32_16x16x32_bf16 v[18:21], v[180:183], v[208:211], v[18:21]
	v_mfma_f32_16x16x32_bf16 v[6:9], v[150:153], v[216:219], v[6:9]
	v_mfma_f32_16x16x32_bf16 v[2:5], v[180:183], v[216:219], v[2:5]
	s_setprio 0
	s_barrier
	s_add_i32 s29, s29, 2
	s_add_u32 s2, s2, 0x100
	s_addc_u32 s3, s3, 0
	s_cmp_gt_u32 s29, 41
	s_mov_b64 s[30:31], s[8:9]
	s_cbranch_scc0 .LBB0_1197
	s_and_b64 vcc, exec, s[20:21]
	s_cbranch_vccz .LBB0_1200
	s_barrier
